# v13 + static s_setprio 1 for the wr==1 (waves 4-7) half in GEMM phases, all per-cluster setprio flips deleted
# speedup vs baseline: 1.0007x; 1.0007x over previous
.LBB0_797:
	s_waitcnt vmcnt(0)
	v_ashrrev_i32_e32 v0, 31, v222
	v_lshrrev_b32_e32 v0, 26, v0
	v_add_u32_e32 v0, v222, v0
	v_ashrrev_i32_e32 v10, 6, v0
	v_bfe_i32 v0, v222, 27, 1
	v_lshlrev_b32_e32 v2, 4, v222
	v_lshrrev_b32_e32 v0, 22, v0
	v_add_u32_e32 v0, v2, v0
	v_and_b32_e32 v0, 0xfffffc00, v0
	v_sub_u32_e32 v0, v2, v0
	v_lshrrev_b32_e32 v3, 4, v0
	v_bitop3_b32 v0, v3, v0, 32 bitop3:0x6c
	s_waitcnt lgkmcnt(0)
	v_ashrrev_i32_e32 v4, 31, v0
	v_lshrrev_b32_e32 v4, 26, v4
	v_add_u32_e32 v4, v0, v4
	v_readlane_b32 s0, v254, 20
	v_lshlrev_b32_e32 v3, 3, v10
	v_ashrrev_i32_e32 v11, 6, v4
	v_and_b32_e32 v4, 0xc0, v4
	v_readlane_b32 s1, v254, 21
	v_and_b32_e32 v3, -16, v3
	v_sub_u32_e32 v0, v0, v4
	s_and_b64 s[0:1], s[0:1], exec
	v_add_u32_e32 v3, v11, v3
	v_ashrrev_i16_sdwa v0, v241, sext(v0) dst_sel:DWORD dst_unused:UNUSED_PAD src0_sel:DWORD src1_sel:BYTE_0
	v_lshlrev_b32_e32 v5, 5, v10
	v_bfe_i32 v12, v0, 0, 16
	v_lshlrev_b32_e32 v0, 1, v3
	v_lshrrev_b32_e32 v4, 2, v3
	v_and_b32_e32 v6, 3, v11
	s_mov_b32 s1, 0x1fffe0
	v_and_b32_e32 v5, 32, v5
	v_and_b32_e32 v0, 24, v0
	v_and_b32_e32 v4, 4, v4
	v_and_or_b32 v6, v3, s1, v6
	v_or3_b32 v0, v6, v4, v0
	v_add_lshl_u32 v4, v5, v12, 1
	v_add_u32_e32 v2, 0x2000, v2
	v_lshl_add_u32 v154, v3, 11, v4
	v_ashrrev_i32_e32 v3, 31, v2
	v_lshrrev_b32_e32 v3, 22, v3
	v_add_u32_e32 v3, v2, v3
	v_ashrrev_i32_e32 v13, 10, v3
	v_mul_i32_i24_e32 v3, 0x400, v13
	v_sub_u32_e32 v2, v2, v3
	v_lshrrev_b32_e32 v3, 4, v2
	v_bitop3_b32 v2, v3, v2, 32 bitop3:0x6c
	v_lshl_add_u32 v0, v0, 11, v4
	v_ashrrev_i32_e32 v4, 31, v2
	s_mov_b32 s0, 0x4300000
	v_lshrrev_b32_e32 v4, 26, v4
	s_cselect_b32 s0, s0, 0x5080000
	v_readlane_b32 s2, v254, 12
	v_lshlrev_b32_e32 v3, 3, v13
	v_add_u32_e32 v4, v2, v4
	v_readlane_b32 s3, v254, 13
	s_add_u32 s34, s2, s0
	v_and_b32_e32 v3, -16, v3
	v_ashrrev_i32_e32 v14, 6, v4
	s_addc_u32 s35, s3, 0
	s_ashr_i32 s0, s5, 6
	v_add_u32_e32 v3, v14, v3
	v_and_b32_e32 v4, 0xc0, v4
	v_and_b32_e32 v6, 3, v14
	s_ashr_i32 s7, s6, 31
	s_ashr_i32 s27, s26, 31
	v_sub_u32_e32 v2, v2, v4
	v_and_or_b32 v6, v3, s1, v6
	s_ashr_i32 s1, s5, 8
	s_lshl_b32 s36, s0, 10
	s_lshl_b64 s[2:3], s[6:7], 19
	s_lshl_b64 s[8:9], s[26:27], 19
	v_ashrrev_i16_sdwa v2, v241, sext(v2) dst_sel:DWORD dst_unused:UNUSED_PAD src0_sel:DWORD src1_sel:BYTE_0
	s_add_u32 s28, s34, s8
	v_lshlrev_b32_e32 v5, 5, v13
	v_bfe_i32 v15, v2, 0, 16
	v_lshlrev_b32_e32 v2, 1, v3
	v_lshrrev_b32_e32 v4, 2, v3
	s_addc_u32 s29, s35, s9
	s_add_i32 s37, s36, 0
	v_and_b32_e32 v5, 32, v5
	v_and_b32_e32 v2, 24, v2
	v_and_b32_e32 v4, 4, v4
	s_add_i32 m0, s37, 0x10000
	v_or3_b32 v2, v6, v4, v2
	v_add_lshl_u32 v4, v5, v15, 1
	global_load_lds_dwordx4 v0, s[28:29]
	s_add_i32 m0, s37, 0x12000
	v_lshl_add_u32 v158, v2, 11, v4
	s_add_u32 s8, s28, 0x40000
	global_load_lds_dwordx4 v158, s[28:29]
	s_addc_u32 s9, s29, 0
	s_add_i32 m0, s37, 0x14000
	v_lshl_add_u32 v156, v3, 11, v4
	global_load_lds_dwordx4 v0, s[8:9]
	s_add_i32 m0, s37, 0x16000
	v_mov_b32_e32 v159, v1
	global_load_lds_dwordx4 v158, s[8:9]
	v_readlane_b32 s8, v254, 28
	v_readlane_b32 s9, v254, 29
	s_add_u32 s8, s8, s2
	s_addc_u32 s9, s9, s3
	s_add_i32 s38, s37, 0x2000
	s_mov_b32 m0, s37
	s_add_u32 s2, s8, 0x40000
	global_load_lds_dwordx4 v154, s[8:9]
	s_mov_b32 m0, s38
	s_addc_u32 s3, s9, 0
	s_add_i32 s39, s37, 0x4000
	global_load_lds_dwordx4 v156, s[8:9]
	s_mov_b32 m0, s39
	s_add_i32 s40, s37, 0x6000
	global_load_lds_dwordx4 v154, s[2:3]
	s_mov_b32 m0, s40
	v_mov_b32_e32 v155, v1
	global_load_lds_dwordx4 v156, s[2:3]
	v_mov_b32_e32 v157, v1
	s_cmp_eq_u32 s1, 1
	v_lshl_add_u64 v[8:9], s[28:29], 0, v[0:1]
	v_lshl_add_u64 v[6:7], s[28:29], 0, v[158:159]
	v_lshl_add_u64 v[2:3], s[8:9], 0, v[154:155]
	s_cselect_b64 s[2:3], -1, 0
	s_cmp_lg_u32 s1, 1
	v_lshl_add_u64 v[4:5], s[8:9], 0, v[156:157]
	s_cbranch_scc1 .LBB0_799
	s_setprio 1
	s_barrier

.LBB0_808:
	s_ashr_i32 s21, s20, 31
	s_lshl_b64 s[22:23], s[20:21], 19
	v_readlane_b32 s24, v254, 28
	v_readlane_b32 s25, v254, 29
	s_add_u32 s22, s24, s22
	s_addc_u32 s23, s25, s23
	s_and_b64 s[24:25], s[4:5], exec
	s_cselect_b32 s7, s23, s9
	s_cselect_b32 s21, s22, s8
	s_ashr_i32 s19, s18, 31
	s_lshl_b64 s[24:25], s[18:19], 19
	s_add_u32 s24, s34, s24
	s_addc_u32 s25, s35, s25
	s_and_b64 s[30:31], s[4:5], exec
	s_cselect_b32 s19, s25, s29
	s_cselect_b32 s27, s24, s28
	s_add_u32 s8, s8, 0x40080
	s_addc_u32 s9, s9, 0
	s_add_u32 s53, s28, 0x100
	s_addc_u32 s54, s29, 0
	s_mov_b32 s55, -2
	s_add_u32 s28, s8, 0xfffc0080
	s_addc_u32 s29, s9, -1
	s_add_i32 s56, 0, 0x10000
	s_cmp_eq_u32 s55, 12
	s_cselect_b32 s31, s7, s29
	s_cselect_b32 s30, s21, s28
	s_cselect_b32 s29, s19, s54
	s_cselect_b32 s28, s27, s53
	s_add_i32 s58, 0, 0x14000
	v_add_u32_e32 v142, s56, v224
	v_add_u32_e32 v162, s58, v224
	ds_read_b128 v[130:133], v142
	ds_read_b128 v[134:137], v142 offset:1024
	ds_read_b128 v[138:141], v142 offset:2048
	ds_read_b128 v[142:145], v142 offset:3072
	ds_read_b128 v[146:149], v162
	ds_read_b128 v[150:153], v162 offset:1024
	ds_read_b128 v[176:179], v162 offset:2048
	ds_read_b128 v[180:183], v162 offset:3072
	v_lshl_add_u64 v[162:163], s[8:9], 0, v[172:173]
	s_add_i32 m0, s37, 0xc000
	ds_read_b128 v[184:187], v226
	ds_read_b128 v[188:191], v226 offset:1024
	ds_read_b128 v[192:195], v226 offset:2048
	ds_read_b128 v[196:199], v226 offset:3072
	ds_read_b128 v[200:203], v226 offset:4096
	ds_read_b128 v[204:207], v226 offset:5120
	ds_read_b128 v[228:231], v226 offset:6144
	ds_read_b128 v[232:235], v226 offset:7168
	global_load_lds_dwordx4 v[162:163], off
	v_lshl_add_u64 v[162:163], s[8:9], 0, v[174:175]
	s_add_i32 m0, s37, 0xe000
	s_nop 0
	global_load_lds_dwordx4 v[162:163], off
	s_waitcnt vmcnt(16)
	s_waitcnt lgkmcnt(0)
	s_barrier
	s_waitcnt lgkmcnt(0)
	v_mfma_f32_16x16x32_bf16 v[126:129], v[130:133], v[184:187], 0
	v_mfma_f32_16x16x32_bf16 v[122:125], v[138:141], v[184:187], 0
	v_mfma_f32_16x16x32_bf16 v[110:113], v[130:133], v[192:195], 0
	v_mfma_f32_16x16x32_bf16 v[106:109], v[138:141], v[192:195], 0
	v_mfma_f32_16x16x32_bf16 v[94:97], v[130:133], v[200:203], 0
	v_mfma_f32_16x16x32_bf16 v[90:93], v[138:141], v[200:203], 0
	v_mfma_f32_16x16x32_bf16 v[78:81], v[130:133], v[228:231], 0
	v_mfma_f32_16x16x32_bf16 v[74:77], v[138:141], v[228:231], 0
	v_mfma_f32_16x16x32_bf16 v[126:129], v[134:137], v[188:191], v[126:129]
	v_mfma_f32_16x16x32_bf16 v[122:125], v[142:145], v[188:191], v[122:125]
	v_mfma_f32_16x16x32_bf16 v[110:113], v[134:137], v[196:199], v[110:113]
	v_mfma_f32_16x16x32_bf16 v[106:109], v[142:145], v[196:199], v[106:109]
	v_mfma_f32_16x16x32_bf16 v[94:97], v[134:137], v[204:207], v[94:97]
	v_mfma_f32_16x16x32_bf16 v[90:93], v[142:145], v[204:207], v[90:93]
	v_mfma_f32_16x16x32_bf16 v[78:81], v[134:137], v[232:235], v[78:81]
	v_mfma_f32_16x16x32_bf16 v[74:77], v[142:145], v[232:235], v[74:77]
	v_mfma_f32_16x16x32_bf16 v[118:121], v[146:149], v[184:187], 0
	v_mfma_f32_16x16x32_bf16 v[114:117], v[176:179], v[184:187], 0
	v_mfma_f32_16x16x32_bf16 v[102:105], v[146:149], v[192:195], 0
	v_mfma_f32_16x16x32_bf16 v[98:101], v[176:179], v[192:195], 0
	v_mfma_f32_16x16x32_bf16 v[86:89], v[146:149], v[200:203], 0
	v_mfma_f32_16x16x32_bf16 v[82:85], v[176:179], v[200:203], 0
	v_mfma_f32_16x16x32_bf16 v[70:73], v[146:149], v[228:231], 0
	v_mfma_f32_16x16x32_bf16 v[66:69], v[176:179], v[228:231], 0
	v_mfma_f32_16x16x32_bf16 v[118:121], v[150:153], v[188:191], v[118:121]
	v_mfma_f32_16x16x32_bf16 v[114:117], v[180:183], v[188:191], v[114:117]
	v_mfma_f32_16x16x32_bf16 v[102:105], v[150:153], v[196:199], v[102:105]
	v_mfma_f32_16x16x32_bf16 v[98:101], v[180:183], v[196:199], v[98:101]
	v_mfma_f32_16x16x32_bf16 v[86:89], v[150:153], v[204:207], v[86:89]
	v_mfma_f32_16x16x32_bf16 v[82:85], v[180:183], v[204:207], v[82:85]
	v_mfma_f32_16x16x32_bf16 v[70:73], v[150:153], v[232:235], v[70:73]
	v_mfma_f32_16x16x32_bf16 v[66:69], v[180:183], v[232:235], v[66:69]
	s_barrier
	s_add_i32 s56, s56, s36
	v_lshl_add_u64 v[162:163], s[28:29], 0, v[0:1]
	s_mov_b32 m0, s56
	ds_read_b128 v[184:187], v226 offset:16384
	ds_read_b128 v[188:191], v226 offset:17408
	ds_read_b128 v[192:195], v226 offset:18432
	ds_read_b128 v[196:199], v226 offset:19456
	ds_read_b128 v[200:203], v226 offset:20480
	ds_read_b128 v[204:207], v226 offset:21504
	ds_read_b128 v[228:231], v226 offset:22528
	ds_read_b128 v[232:235], v226 offset:23552
	global_load_lds_dwordx4 v[162:163], off
	s_add_i32 m0, s56, 0x2000
	s_add_u32 s56, s28, 0x40000
	v_lshl_add_u64 v[208:209], s[28:29], 0, v[158:159]
	s_addc_u32 s57, s29, 0
	s_add_i32 s58, s58, s36
	global_load_lds_dwordx4 v[208:209], off
	v_lshl_add_u64 v[214:215], s[56:57], 0, v[0:1]
	s_mov_b32 m0, s58
	v_lshl_add_u64 v[216:217], s[30:31], 0, v[156:157]
	global_load_lds_dwordx4 v[214:215], off
	v_lshl_add_u64 v[214:215], s[56:57], 0, v[158:159]
	s_add_i32 m0, s58, 0x2000
	s_nop 0
	global_load_lds_dwordx4 v[214:215], off
	v_lshl_add_u64 v[214:215], s[30:31], 0, v[154:155]
	s_mov_b32 m0, s37
	s_nop 0
	global_load_lds_dwordx4 v[214:215], off
	s_mov_b32 m0, s38
	s_nop 0
	global_load_lds_dwordx4 v[216:217], off
	s_cmp_eq_u32 s46, 1
	s_cbranch_scc1 .Lpj_peel_w8
	s_waitcnt vmcnt(16)
	s_branch .Lpj_peel_wj

.Lpj_peel_wj:
	s_waitcnt lgkmcnt(0)
	s_barrier
	s_waitcnt lgkmcnt(0)
	v_mfma_f32_16x16x32_bf16 v[62:65], v[130:133], v[184:187], 0
	v_mfma_f32_16x16x32_bf16 v[58:61], v[138:141], v[184:187], 0
	v_mfma_f32_16x16x32_bf16 v[46:49], v[130:133], v[192:195], 0
	v_mfma_f32_16x16x32_bf16 v[42:45], v[138:141], v[192:195], 0
	v_mfma_f32_16x16x32_bf16 v[30:33], v[130:133], v[200:203], 0
	v_mfma_f32_16x16x32_bf16 v[26:29], v[138:141], v[200:203], 0
	v_mfma_f32_16x16x32_bf16 v[14:17], v[130:133], v[228:231], 0
	v_mfma_f32_16x16x32_bf16 v[10:13], v[138:141], v[228:231], 0
	v_mfma_f32_16x16x32_bf16 v[62:65], v[134:137], v[188:191], v[62:65]
	v_mfma_f32_16x16x32_bf16 v[58:61], v[142:145], v[188:191], v[58:61]
	v_mfma_f32_16x16x32_bf16 v[46:49], v[134:137], v[196:199], v[46:49]
	v_mfma_f32_16x16x32_bf16 v[42:45], v[142:145], v[196:199], v[42:45]
	v_mfma_f32_16x16x32_bf16 v[30:33], v[134:137], v[204:207], v[30:33]
	v_mfma_f32_16x16x32_bf16 v[26:29], v[142:145], v[204:207], v[26:29]
	v_mfma_f32_16x16x32_bf16 v[14:17], v[134:137], v[232:235], v[14:17]
	v_mfma_f32_16x16x32_bf16 v[10:13], v[142:145], v[232:235], v[10:13]
	v_mfma_f32_16x16x32_bf16 v[54:57], v[146:149], v[184:187], 0
	v_mfma_f32_16x16x32_bf16 v[50:53], v[176:179], v[184:187], 0
	v_mfma_f32_16x16x32_bf16 v[38:41], v[146:149], v[192:195], 0
	v_mfma_f32_16x16x32_bf16 v[34:37], v[176:179], v[192:195], 0
	v_mfma_f32_16x16x32_bf16 v[22:25], v[146:149], v[200:203], 0
	v_mfma_f32_16x16x32_bf16 v[18:21], v[176:179], v[200:203], 0
	v_mfma_f32_16x16x32_bf16 v[6:9], v[146:149], v[228:231], 0
	v_mfma_f32_16x16x32_bf16 v[2:5], v[176:179], v[228:231], 0
	v_mfma_f32_16x16x32_bf16 v[54:57], v[150:153], v[188:191], v[54:57]
	v_mfma_f32_16x16x32_bf16 v[50:53], v[180:183], v[188:191], v[50:53]
	v_mfma_f32_16x16x32_bf16 v[38:41], v[150:153], v[196:199], v[38:41]
	v_mfma_f32_16x16x32_bf16 v[34:37], v[180:183], v[196:199], v[34:37]
	v_mfma_f32_16x16x32_bf16 v[22:25], v[150:153], v[204:207], v[22:25]
	v_mfma_f32_16x16x32_bf16 v[18:21], v[180:183], v[204:207], v[18:21]
	v_mfma_f32_16x16x32_bf16 v[6:9], v[150:153], v[232:235], v[6:9]
	v_mfma_f32_16x16x32_bf16 v[2:5], v[180:183], v[232:235], v[2:5]
	s_barrier
	s_add_i32 s56, 0, 0x18000
	s_add_i32 s57, 0, 0x1c000
	v_add_u32_e32 v142, s56, v224
	v_add_u32_e32 v164, s57, v224
	ds_read_b128 v[130:133], v142
	ds_read_b128 v[134:137], v142 offset:1024
	ds_read_b128 v[138:141], v142 offset:2048
	ds_read_b128 v[142:145], v142 offset:3072
	ds_read_b128 v[146:149], v164
	ds_read_b128 v[150:153], v164 offset:1024
	ds_read_b128 v[176:179], v164 offset:2048
	ds_read_b128 v[180:183], v164 offset:3072
	s_add_u32 s30, s30, 0x40000
	s_addc_u32 s31, s31, 0
	s_mov_b32 m0, s39
	v_lshl_add_u64 v[236:237], s[30:31], 0, v[154:155]
	ds_read_b128 v[184:187], v226 offset:32768
	ds_read_b128 v[188:191], v226 offset:33792
	ds_read_b128 v[192:195], v226 offset:34816
	ds_read_b128 v[196:199], v226 offset:35840
	ds_read_b128 v[200:203], v226 offset:36864
	ds_read_b128 v[204:207], v226 offset:37888
	ds_read_b128 v[228:231], v226 offset:38912
	ds_read_b128 v[232:235], v226 offset:39936
	global_load_lds_dwordx4 v[236:237], off
	v_lshl_add_u64 v[236:237], s[30:31], 0, v[156:157]
	s_mov_b32 m0, s40
	s_nop 0
	global_load_lds_dwordx4 v[236:237], off
	s_waitcnt vmcnt(8)
	s_waitcnt lgkmcnt(0)
	s_barrier
	s_waitcnt lgkmcnt(0)
	v_mfma_f32_16x16x32_bf16 v[126:129], v[130:133], v[184:187], v[126:129]
	v_mfma_f32_16x16x32_bf16 v[122:125], v[138:141], v[184:187], v[122:125]
	v_mfma_f32_16x16x32_bf16 v[110:113], v[130:133], v[192:195], v[110:113]
	v_mfma_f32_16x16x32_bf16 v[106:109], v[138:141], v[192:195], v[106:109]
	v_mfma_f32_16x16x32_bf16 v[94:97], v[130:133], v[200:203], v[94:97]
	v_mfma_f32_16x16x32_bf16 v[90:93], v[138:141], v[200:203], v[90:93]
	v_mfma_f32_16x16x32_bf16 v[78:81], v[130:133], v[228:231], v[78:81]
	v_mfma_f32_16x16x32_bf16 v[74:77], v[138:141], v[228:231], v[74:77]
	v_mfma_f32_16x16x32_bf16 v[126:129], v[134:137], v[188:191], v[126:129]
	v_mfma_f32_16x16x32_bf16 v[122:125], v[142:145], v[188:191], v[122:125]
	v_mfma_f32_16x16x32_bf16 v[110:113], v[134:137], v[196:199], v[110:113]
	v_mfma_f32_16x16x32_bf16 v[106:109], v[142:145], v[196:199], v[106:109]
	v_mfma_f32_16x16x32_bf16 v[94:97], v[134:137], v[204:207], v[94:97]
	v_mfma_f32_16x16x32_bf16 v[90:93], v[142:145], v[204:207], v[90:93]
	v_mfma_f32_16x16x32_bf16 v[78:81], v[134:137], v[232:235], v[78:81]
	v_mfma_f32_16x16x32_bf16 v[74:77], v[142:145], v[232:235], v[74:77]
	v_mfma_f32_16x16x32_bf16 v[118:121], v[146:149], v[184:187], v[118:121]
	v_mfma_f32_16x16x32_bf16 v[114:117], v[176:179], v[184:187], v[114:117]
	v_mfma_f32_16x16x32_bf16 v[102:105], v[146:149], v[192:195], v[102:105]
	v_mfma_f32_16x16x32_bf16 v[98:101], v[176:179], v[192:195], v[98:101]
	v_mfma_f32_16x16x32_bf16 v[86:89], v[146:149], v[200:203], v[86:89]
	v_mfma_f32_16x16x32_bf16 v[82:85], v[176:179], v[200:203], v[82:85]
	v_mfma_f32_16x16x32_bf16 v[70:73], v[146:149], v[228:231], v[70:73]
	v_mfma_f32_16x16x32_bf16 v[66:69], v[176:179], v[228:231], v[66:69]
	v_mfma_f32_16x16x32_bf16 v[118:121], v[150:153], v[188:191], v[118:121]
	v_mfma_f32_16x16x32_bf16 v[114:117], v[180:183], v[188:191], v[114:117]
	v_mfma_f32_16x16x32_bf16 v[102:105], v[150:153], v[196:199], v[102:105]
	v_mfma_f32_16x16x32_bf16 v[98:101], v[180:183], v[196:199], v[98:101]
	v_mfma_f32_16x16x32_bf16 v[86:89], v[150:153], v[204:207], v[86:89]
	v_mfma_f32_16x16x32_bf16 v[82:85], v[180:183], v[204:207], v[82:85]
	v_mfma_f32_16x16x32_bf16 v[70:73], v[150:153], v[232:235], v[70:73]
	v_mfma_f32_16x16x32_bf16 v[66:69], v[180:183], v[232:235], v[66:69]
	s_barrier
	s_add_i32 s30, s56, s36
	v_lshl_add_u64 v[162:163], v[162:163], 0, s[86:87]
	s_mov_b32 m0, s30
	ds_read_b128 v[184:187], v226 offset:49152
	ds_read_b128 v[188:191], v226 offset:50176
	ds_read_b128 v[192:195], v226 offset:51200
	ds_read_b128 v[196:199], v226 offset:52224
	ds_read_b128 v[200:203], v226 offset:53248
	ds_read_b128 v[204:207], v226 offset:54272
	ds_read_b128 v[228:231], v226 offset:55296
	ds_read_b128 v[232:235], v226 offset:56320
	global_load_lds_dwordx4 v[162:163], off
	s_add_i32 m0, s30, 0x2000
	s_add_u32 s28, s28, 0x40080
	v_lshl_add_u64 v[162:163], v[208:209], 0, s[86:87]
	s_addc_u32 s29, s29, 0
	s_add_i32 s30, s57, s36
	global_load_lds_dwordx4 v[162:163], off
	v_lshl_add_u64 v[162:163], s[28:29], 0, v[0:1]
	s_mov_b32 m0, s30
	s_nop 0
	global_load_lds_dwordx4 v[162:163], off
	v_lshl_add_u64 v[162:163], s[28:29], 0, v[158:159]
	s_add_i32 m0, s30, 0x2000
	s_nop 0
	global_load_lds_dwordx4 v[162:163], off
	v_lshl_add_u64 v[162:163], v[214:215], 0, s[86:87]
	s_mov_b32 m0, s44
	s_nop 0
	global_load_lds_dwordx4 v[162:163], off
	v_lshl_add_u64 v[162:163], v[216:217], 0, s[86:87]
	s_mov_b32 m0, s45
	s_nop 0
	global_load_lds_dwordx4 v[162:163], off
	s_waitcnt vmcnt(8)
	s_waitcnt lgkmcnt(0)
	s_barrier
	s_waitcnt lgkmcnt(0)
	v_mfma_f32_16x16x32_bf16 v[62:65], v[130:133], v[184:187], v[62:65]
	v_mfma_f32_16x16x32_bf16 v[58:61], v[138:141], v[184:187], v[58:61]
	v_mfma_f32_16x16x32_bf16 v[46:49], v[130:133], v[192:195], v[46:49]
	v_mfma_f32_16x16x32_bf16 v[42:45], v[138:141], v[192:195], v[42:45]
	v_mfma_f32_16x16x32_bf16 v[30:33], v[130:133], v[200:203], v[30:33]
	v_mfma_f32_16x16x32_bf16 v[26:29], v[138:141], v[200:203], v[26:29]
	v_mfma_f32_16x16x32_bf16 v[14:17], v[130:133], v[228:231], v[14:17]
	v_mfma_f32_16x16x32_bf16 v[10:13], v[138:141], v[228:231], v[10:13]
	v_mfma_f32_16x16x32_bf16 v[62:65], v[134:137], v[188:191], v[62:65]
	v_mfma_f32_16x16x32_bf16 v[58:61], v[142:145], v[188:191], v[58:61]
	v_mfma_f32_16x16x32_bf16 v[46:49], v[134:137], v[196:199], v[46:49]
	v_mfma_f32_16x16x32_bf16 v[42:45], v[142:145], v[196:199], v[42:45]
	v_mfma_f32_16x16x32_bf16 v[30:33], v[134:137], v[204:207], v[30:33]
	v_mfma_f32_16x16x32_bf16 v[26:29], v[142:145], v[204:207], v[26:29]
	v_mfma_f32_16x16x32_bf16 v[14:17], v[134:137], v[232:235], v[14:17]
	v_mfma_f32_16x16x32_bf16 v[10:13], v[142:145], v[232:235], v[10:13]
	v_mfma_f32_16x16x32_bf16 v[54:57], v[146:149], v[184:187], v[54:57]
	v_mfma_f32_16x16x32_bf16 v[50:53], v[176:179], v[184:187], v[50:53]
	v_mfma_f32_16x16x32_bf16 v[38:41], v[146:149], v[192:195], v[38:41]
	v_mfma_f32_16x16x32_bf16 v[34:37], v[176:179], v[192:195], v[34:37]
	v_mfma_f32_16x16x32_bf16 v[22:25], v[146:149], v[200:203], v[22:25]
	v_mfma_f32_16x16x32_bf16 v[18:21], v[176:179], v[200:203], v[18:21]
	v_mfma_f32_16x16x32_bf16 v[6:9], v[146:149], v[228:231], v[6:9]
	v_mfma_f32_16x16x32_bf16 v[2:5], v[176:179], v[228:231], v[2:5]
	v_mfma_f32_16x16x32_bf16 v[54:57], v[150:153], v[188:191], v[54:57]
	v_mfma_f32_16x16x32_bf16 v[50:53], v[180:183], v[188:191], v[50:53]
	v_mfma_f32_16x16x32_bf16 v[38:41], v[150:153], v[196:199], v[38:41]
	v_mfma_f32_16x16x32_bf16 v[34:37], v[180:183], v[196:199], v[34:37]
	v_mfma_f32_16x16x32_bf16 v[22:25], v[150:153], v[204:207], v[22:25]
	v_mfma_f32_16x16x32_bf16 v[18:21], v[180:183], v[204:207], v[18:21]
	v_mfma_f32_16x16x32_bf16 v[6:9], v[150:153], v[232:235], v[6:9]
	v_mfma_f32_16x16x32_bf16 v[2:5], v[180:183], v[232:235], v[2:5]
	s_barrier
	s_add_i32 s55, s55, 2
	s_add_u32 s8, s8, 0x100
	s_addc_u32 s9, s9, 0
	s_add_u32 s53, s53, 0x100
	s_addc_u32 s54, s54, 0
	s_cmp_gt_u32 s55, 13
	s_cbranch_scc0 .LBB0_809
.LBB0_809:
	s_add_u32 s28, s8, 0xfffc0080
	s_addc_u32 s29, s9, -1
	s_add_i32 s56, 0, 0x10000
	s_cmp_eq_u32 s55, 12
	s_cselect_b32 s31, s7, s29
	s_cselect_b32 s30, s21, s28
	s_cselect_b32 s29, s19, s54
	s_cselect_b32 s28, s27, s53
	s_add_i32 s58, 0, 0x14000
	v_add_u32_e32 v142, s56, v224
	v_add_u32_e32 v162, s58, v224
	ds_read_b128 v[130:133], v142
	ds_read_b128 v[134:137], v142 offset:1024
	ds_read_b128 v[138:141], v142 offset:2048
	ds_read_b128 v[142:145], v142 offset:3072
	ds_read_b128 v[146:149], v162
	ds_read_b128 v[150:153], v162 offset:1024
	ds_read_b128 v[176:179], v162 offset:2048
	ds_read_b128 v[180:183], v162 offset:3072
	v_lshl_add_u64 v[162:163], s[8:9], 0, v[172:173]
	s_add_i32 m0, s37, 0xc000
	ds_read_b128 v[184:187], v226
	ds_read_b128 v[188:191], v226 offset:1024
	ds_read_b128 v[192:195], v226 offset:2048
	ds_read_b128 v[196:199], v226 offset:3072
	ds_read_b128 v[200:203], v226 offset:4096
	ds_read_b128 v[204:207], v226 offset:5120
	ds_read_b128 v[228:231], v226 offset:6144
	ds_read_b128 v[232:235], v226 offset:7168
	global_load_lds_dwordx4 v[162:163], off
	v_lshl_add_u64 v[162:163], s[8:9], 0, v[174:175]
	s_add_i32 m0, s37, 0xe000
	s_nop 0
	global_load_lds_dwordx4 v[162:163], off
	s_waitcnt vmcnt(8)
	s_waitcnt lgkmcnt(0)
	s_barrier
	s_waitcnt lgkmcnt(0)
	v_mfma_f32_16x16x32_bf16 v[126:129], v[130:133], v[184:187], v[126:129]
	v_mfma_f32_16x16x32_bf16 v[122:125], v[138:141], v[184:187], v[122:125]
	v_mfma_f32_16x16x32_bf16 v[110:113], v[130:133], v[192:195], v[110:113]
	v_mfma_f32_16x16x32_bf16 v[106:109], v[138:141], v[192:195], v[106:109]
	v_mfma_f32_16x16x32_bf16 v[94:97], v[130:133], v[200:203], v[94:97]
	v_mfma_f32_16x16x32_bf16 v[90:93], v[138:141], v[200:203], v[90:93]
	v_mfma_f32_16x16x32_bf16 v[78:81], v[130:133], v[228:231], v[78:81]
	v_mfma_f32_16x16x32_bf16 v[74:77], v[138:141], v[228:231], v[74:77]
	v_mfma_f32_16x16x32_bf16 v[126:129], v[134:137], v[188:191], v[126:129]
	v_mfma_f32_16x16x32_bf16 v[122:125], v[142:145], v[188:191], v[122:125]
	v_mfma_f32_16x16x32_bf16 v[110:113], v[134:137], v[196:199], v[110:113]
	v_mfma_f32_16x16x32_bf16 v[106:109], v[142:145], v[196:199], v[106:109]
	v_mfma_f32_16x16x32_bf16 v[94:97], v[134:137], v[204:207], v[94:97]
	v_mfma_f32_16x16x32_bf16 v[90:93], v[142:145], v[204:207], v[90:93]
	v_mfma_f32_16x16x32_bf16 v[78:81], v[134:137], v[232:235], v[78:81]
	v_mfma_f32_16x16x32_bf16 v[74:77], v[142:145], v[232:235], v[74:77]
	v_mfma_f32_16x16x32_bf16 v[118:121], v[146:149], v[184:187], v[118:121]
	v_mfma_f32_16x16x32_bf16 v[114:117], v[176:179], v[184:187], v[114:117]
	v_mfma_f32_16x16x32_bf16 v[102:105], v[146:149], v[192:195], v[102:105]
	v_mfma_f32_16x16x32_bf16 v[98:101], v[176:179], v[192:195], v[98:101]
	v_mfma_f32_16x16x32_bf16 v[86:89], v[146:149], v[200:203], v[86:89]
	v_mfma_f32_16x16x32_bf16 v[82:85], v[176:179], v[200:203], v[82:85]
	v_mfma_f32_16x16x32_bf16 v[70:73], v[146:149], v[228:231], v[70:73]
	v_mfma_f32_16x16x32_bf16 v[66:69], v[176:179], v[228:231], v[66:69]
	v_mfma_f32_16x16x32_bf16 v[118:121], v[150:153], v[188:191], v[118:121]
	v_mfma_f32_16x16x32_bf16 v[114:117], v[180:183], v[188:191], v[114:117]
	v_mfma_f32_16x16x32_bf16 v[102:105], v[150:153], v[196:199], v[102:105]
	v_mfma_f32_16x16x32_bf16 v[98:101], v[180:183], v[196:199], v[98:101]
	v_mfma_f32_16x16x32_bf16 v[86:89], v[150:153], v[204:207], v[86:89]
	v_mfma_f32_16x16x32_bf16 v[82:85], v[180:183], v[204:207], v[82:85]
	v_mfma_f32_16x16x32_bf16 v[70:73], v[150:153], v[232:235], v[70:73]
	v_mfma_f32_16x16x32_bf16 v[66:69], v[180:183], v[232:235], v[66:69]
	s_barrier
	s_add_i32 s56, s56, s36
	v_lshl_add_u64 v[162:163], s[28:29], 0, v[0:1]
	s_mov_b32 m0, s56
	ds_read_b128 v[184:187], v226 offset:16384
	ds_read_b128 v[188:191], v226 offset:17408
	ds_read_b128 v[192:195], v226 offset:18432
	ds_read_b128 v[196:199], v226 offset:19456
	ds_read_b128 v[200:203], v226 offset:20480
	ds_read_b128 v[204:207], v226 offset:21504
	ds_read_b128 v[228:231], v226 offset:22528
	ds_read_b128 v[232:235], v226 offset:23552
	global_load_lds_dwordx4 v[162:163], off
	s_add_i32 m0, s56, 0x2000
	s_add_u32 s56, s28, 0x40000
	v_lshl_add_u64 v[208:209], s[28:29], 0, v[158:159]
	s_addc_u32 s57, s29, 0
	s_add_i32 s58, s58, s36
	global_load_lds_dwordx4 v[208:209], off
	v_lshl_add_u64 v[214:215], s[56:57], 0, v[0:1]
	s_mov_b32 m0, s58
	v_lshl_add_u64 v[216:217], s[30:31], 0, v[156:157]
	global_load_lds_dwordx4 v[214:215], off
	v_lshl_add_u64 v[214:215], s[56:57], 0, v[158:159]
	s_add_i32 m0, s58, 0x2000
	s_nop 0
	global_load_lds_dwordx4 v[214:215], off
	v_lshl_add_u64 v[214:215], s[30:31], 0, v[154:155]
	s_mov_b32 m0, s37
	s_nop 0
	global_load_lds_dwordx4 v[214:215], off
	s_mov_b32 m0, s38
	s_nop 0
	global_load_lds_dwordx4 v[216:217], off
	s_waitcnt vmcnt(8)
	s_waitcnt lgkmcnt(0)
	s_barrier
	s_waitcnt lgkmcnt(0)
	v_mfma_f32_16x16x32_bf16 v[62:65], v[130:133], v[184:187], v[62:65]
	v_mfma_f32_16x16x32_bf16 v[58:61], v[138:141], v[184:187], v[58:61]
	v_mfma_f32_16x16x32_bf16 v[46:49], v[130:133], v[192:195], v[46:49]
	v_mfma_f32_16x16x32_bf16 v[42:45], v[138:141], v[192:195], v[42:45]
	v_mfma_f32_16x16x32_bf16 v[30:33], v[130:133], v[200:203], v[30:33]
	v_mfma_f32_16x16x32_bf16 v[26:29], v[138:141], v[200:203], v[26:29]
	v_mfma_f32_16x16x32_bf16 v[14:17], v[130:133], v[228:231], v[14:17]
	v_mfma_f32_16x16x32_bf16 v[10:13], v[138:141], v[228:231], v[10:13]
	v_mfma_f32_16x16x32_bf16 v[62:65], v[134:137], v[188:191], v[62:65]
	v_mfma_f32_16x16x32_bf16 v[58:61], v[142:145], v[188:191], v[58:61]
	v_mfma_f32_16x16x32_bf16 v[46:49], v[134:137], v[196:199], v[46:49]
	v_mfma_f32_16x16x32_bf16 v[42:45], v[142:145], v[196:199], v[42:45]
	v_mfma_f32_16x16x32_bf16 v[30:33], v[134:137], v[204:207], v[30:33]
	v_mfma_f32_16x16x32_bf16 v[26:29], v[142:145], v[204:207], v[26:29]
	v_mfma_f32_16x16x32_bf16 v[14:17], v[134:137], v[232:235], v[14:17]
	v_mfma_f32_16x16x32_bf16 v[10:13], v[142:145], v[232:235], v[10:13]
	v_mfma_f32_16x16x32_bf16 v[54:57], v[146:149], v[184:187], v[54:57]
	v_mfma_f32_16x16x32_bf16 v[50:53], v[176:179], v[184:187], v[50:53]
	v_mfma_f32_16x16x32_bf16 v[38:41], v[146:149], v[192:195], v[38:41]
	v_mfma_f32_16x16x32_bf16 v[34:37], v[176:179], v[192:195], v[34:37]
	v_mfma_f32_16x16x32_bf16 v[22:25], v[146:149], v[200:203], v[22:25]
	v_mfma_f32_16x16x32_bf16 v[18:21], v[176:179], v[200:203], v[18:21]
	v_mfma_f32_16x16x32_bf16 v[6:9], v[146:149], v[228:231], v[6:9]
	v_mfma_f32_16x16x32_bf16 v[2:5], v[176:179], v[228:231], v[2:5]
	v_mfma_f32_16x16x32_bf16 v[54:57], v[150:153], v[188:191], v[54:57]
	v_mfma_f32_16x16x32_bf16 v[50:53], v[180:183], v[188:191], v[50:53]
	v_mfma_f32_16x16x32_bf16 v[38:41], v[150:153], v[196:199], v[38:41]
	v_mfma_f32_16x16x32_bf16 v[34:37], v[180:183], v[196:199], v[34:37]
	v_mfma_f32_16x16x32_bf16 v[22:25], v[150:153], v[204:207], v[22:25]
	v_mfma_f32_16x16x32_bf16 v[18:21], v[180:183], v[204:207], v[18:21]
	v_mfma_f32_16x16x32_bf16 v[6:9], v[150:153], v[232:235], v[6:9]
	v_mfma_f32_16x16x32_bf16 v[2:5], v[180:183], v[232:235], v[2:5]
	s_barrier
	s_add_i32 s56, 0, 0x18000
	s_add_i32 s57, 0, 0x1c000
	v_add_u32_e32 v142, s56, v224
	v_add_u32_e32 v164, s57, v224
	ds_read_b128 v[130:133], v142
	ds_read_b128 v[134:137], v142 offset:1024
	ds_read_b128 v[138:141], v142 offset:2048
	ds_read_b128 v[142:145], v142 offset:3072
	ds_read_b128 v[146:149], v164
	ds_read_b128 v[150:153], v164 offset:1024
	ds_read_b128 v[176:179], v164 offset:2048
	ds_read_b128 v[180:183], v164 offset:3072
	s_add_u32 s30, s30, 0x40000
	s_addc_u32 s31, s31, 0
	s_mov_b32 m0, s39
	v_lshl_add_u64 v[236:237], s[30:31], 0, v[154:155]
	ds_read_b128 v[184:187], v226 offset:32768
	ds_read_b128 v[188:191], v226 offset:33792
	ds_read_b128 v[192:195], v226 offset:34816
	ds_read_b128 v[196:199], v226 offset:35840
	ds_read_b128 v[200:203], v226 offset:36864
	ds_read_b128 v[204:207], v226 offset:37888
	ds_read_b128 v[228:231], v226 offset:38912
	ds_read_b128 v[232:235], v226 offset:39936
	global_load_lds_dwordx4 v[236:237], off
	v_lshl_add_u64 v[236:237], s[30:31], 0, v[156:157]
	s_mov_b32 m0, s40
	s_nop 0
	global_load_lds_dwordx4 v[236:237], off
	s_waitcnt vmcnt(8)
	s_waitcnt lgkmcnt(0)
	s_barrier
	s_waitcnt lgkmcnt(0)
	v_mfma_f32_16x16x32_bf16 v[126:129], v[130:133], v[184:187], v[126:129]
	v_mfma_f32_16x16x32_bf16 v[122:125], v[138:141], v[184:187], v[122:125]
	v_mfma_f32_16x16x32_bf16 v[110:113], v[130:133], v[192:195], v[110:113]
	v_mfma_f32_16x16x32_bf16 v[106:109], v[138:141], v[192:195], v[106:109]
	v_mfma_f32_16x16x32_bf16 v[94:97], v[130:133], v[200:203], v[94:97]
	v_mfma_f32_16x16x32_bf16 v[90:93], v[138:141], v[200:203], v[90:93]
	v_mfma_f32_16x16x32_bf16 v[78:81], v[130:133], v[228:231], v[78:81]
	v_mfma_f32_16x16x32_bf16 v[74:77], v[138:141], v[228:231], v[74:77]
	v_mfma_f32_16x16x32_bf16 v[126:129], v[134:137], v[188:191], v[126:129]
	v_mfma_f32_16x16x32_bf16 v[122:125], v[142:145], v[188:191], v[122:125]
	v_mfma_f32_16x16x32_bf16 v[110:113], v[134:137], v[196:199], v[110:113]
	v_mfma_f32_16x16x32_bf16 v[106:109], v[142:145], v[196:199], v[106:109]
	v_mfma_f32_16x16x32_bf16 v[94:97], v[134:137], v[204:207], v[94:97]
	v_mfma_f32_16x16x32_bf16 v[90:93], v[142:145], v[204:207], v[90:93]
	v_mfma_f32_16x16x32_bf16 v[78:81], v[134:137], v[232:235], v[78:81]
	v_mfma_f32_16x16x32_bf16 v[74:77], v[142:145], v[232:235], v[74:77]
	v_mfma_f32_16x16x32_bf16 v[118:121], v[146:149], v[184:187], v[118:121]
	v_mfma_f32_16x16x32_bf16 v[114:117], v[176:179], v[184:187], v[114:117]
	v_mfma_f32_16x16x32_bf16 v[102:105], v[146:149], v[192:195], v[102:105]
	v_mfma_f32_16x16x32_bf16 v[98:101], v[176:179], v[192:195], v[98:101]
	v_mfma_f32_16x16x32_bf16 v[86:89], v[146:149], v[200:203], v[86:89]
	v_mfma_f32_16x16x32_bf16 v[82:85], v[176:179], v[200:203], v[82:85]
	v_mfma_f32_16x16x32_bf16 v[70:73], v[146:149], v[228:231], v[70:73]
	v_mfma_f32_16x16x32_bf16 v[66:69], v[176:179], v[228:231], v[66:69]
	v_mfma_f32_16x16x32_bf16 v[118:121], v[150:153], v[188:191], v[118:121]
	v_mfma_f32_16x16x32_bf16 v[114:117], v[180:183], v[188:191], v[114:117]
	v_mfma_f32_16x16x32_bf16 v[102:105], v[150:153], v[196:199], v[102:105]
	v_mfma_f32_16x16x32_bf16 v[98:101], v[180:183], v[196:199], v[98:101]
	v_mfma_f32_16x16x32_bf16 v[86:89], v[150:153], v[204:207], v[86:89]
	v_mfma_f32_16x16x32_bf16 v[82:85], v[180:183], v[204:207], v[82:85]
	v_mfma_f32_16x16x32_bf16 v[70:73], v[150:153], v[232:235], v[70:73]
	v_mfma_f32_16x16x32_bf16 v[66:69], v[180:183], v[232:235], v[66:69]
	s_barrier
	s_add_i32 s30, s56, s36
	v_lshl_add_u64 v[162:163], v[162:163], 0, s[86:87]
	s_mov_b32 m0, s30
	ds_read_b128 v[184:187], v226 offset:49152
	ds_read_b128 v[188:191], v226 offset:50176
	ds_read_b128 v[192:195], v226 offset:51200
	ds_read_b128 v[196:199], v226 offset:52224
	ds_read_b128 v[200:203], v226 offset:53248
	ds_read_b128 v[204:207], v226 offset:54272
	ds_read_b128 v[228:231], v226 offset:55296
	ds_read_b128 v[232:235], v226 offset:56320
	global_load_lds_dwordx4 v[162:163], off
	s_add_i32 m0, s30, 0x2000
	s_add_u32 s28, s28, 0x40080
	v_lshl_add_u64 v[162:163], v[208:209], 0, s[86:87]
	s_addc_u32 s29, s29, 0
	s_add_i32 s30, s57, s36
	global_load_lds_dwordx4 v[162:163], off
	v_lshl_add_u64 v[162:163], s[28:29], 0, v[0:1]
	s_mov_b32 m0, s30
	s_nop 0
	global_load_lds_dwordx4 v[162:163], off
	v_lshl_add_u64 v[162:163], s[28:29], 0, v[158:159]
	s_add_i32 m0, s30, 0x2000
	s_nop 0
	global_load_lds_dwordx4 v[162:163], off
	v_lshl_add_u64 v[162:163], v[214:215], 0, s[86:87]
	s_mov_b32 m0, s44
	s_nop 0
	global_load_lds_dwordx4 v[162:163], off
	v_lshl_add_u64 v[162:163], v[216:217], 0, s[86:87]
	s_mov_b32 m0, s45
	s_nop 0
	global_load_lds_dwordx4 v[162:163], off
	s_waitcnt vmcnt(8)
	s_waitcnt lgkmcnt(0)
	s_barrier
	s_waitcnt lgkmcnt(0)
	v_mfma_f32_16x16x32_bf16 v[62:65], v[130:133], v[184:187], v[62:65]
	v_mfma_f32_16x16x32_bf16 v[58:61], v[138:141], v[184:187], v[58:61]
	v_mfma_f32_16x16x32_bf16 v[46:49], v[130:133], v[192:195], v[46:49]
	v_mfma_f32_16x16x32_bf16 v[42:45], v[138:141], v[192:195], v[42:45]
	v_mfma_f32_16x16x32_bf16 v[30:33], v[130:133], v[200:203], v[30:33]
	v_mfma_f32_16x16x32_bf16 v[26:29], v[138:141], v[200:203], v[26:29]
	v_mfma_f32_16x16x32_bf16 v[14:17], v[130:133], v[228:231], v[14:17]
	v_mfma_f32_16x16x32_bf16 v[10:13], v[138:141], v[228:231], v[10:13]
	v_mfma_f32_16x16x32_bf16 v[62:65], v[134:137], v[188:191], v[62:65]
	v_mfma_f32_16x16x32_bf16 v[58:61], v[142:145], v[188:191], v[58:61]
	v_mfma_f32_16x16x32_bf16 v[46:49], v[134:137], v[196:199], v[46:49]
	v_mfma_f32_16x16x32_bf16 v[42:45], v[142:145], v[196:199], v[42:45]
	v_mfma_f32_16x16x32_bf16 v[30:33], v[134:137], v[204:207], v[30:33]
	v_mfma_f32_16x16x32_bf16 v[26:29], v[142:145], v[204:207], v[26:29]
	v_mfma_f32_16x16x32_bf16 v[14:17], v[134:137], v[232:235], v[14:17]
	v_mfma_f32_16x16x32_bf16 v[10:13], v[142:145], v[232:235], v[10:13]
	v_mfma_f32_16x16x32_bf16 v[54:57], v[146:149], v[184:187], v[54:57]
	v_mfma_f32_16x16x32_bf16 v[50:53], v[176:179], v[184:187], v[50:53]
	v_mfma_f32_16x16x32_bf16 v[38:41], v[146:149], v[192:195], v[38:41]
	v_mfma_f32_16x16x32_bf16 v[34:37], v[176:179], v[192:195], v[34:37]
	v_mfma_f32_16x16x32_bf16 v[22:25], v[146:149], v[200:203], v[22:25]
	v_mfma_f32_16x16x32_bf16 v[18:21], v[176:179], v[200:203], v[18:21]
	v_mfma_f32_16x16x32_bf16 v[6:9], v[146:149], v[228:231], v[6:9]
	v_mfma_f32_16x16x32_bf16 v[2:5], v[176:179], v[228:231], v[2:5]
	v_mfma_f32_16x16x32_bf16 v[54:57], v[150:153], v[188:191], v[54:57]
	v_mfma_f32_16x16x32_bf16 v[50:53], v[180:183], v[188:191], v[50:53]
	v_mfma_f32_16x16x32_bf16 v[38:41], v[150:153], v[196:199], v[38:41]
	v_mfma_f32_16x16x32_bf16 v[34:37], v[180:183], v[196:199], v[34:37]
	v_mfma_f32_16x16x32_bf16 v[22:25], v[150:153], v[204:207], v[22:25]
	v_mfma_f32_16x16x32_bf16 v[18:21], v[180:183], v[204:207], v[18:21]
	v_mfma_f32_16x16x32_bf16 v[6:9], v[150:153], v[232:235], v[6:9]
	v_mfma_f32_16x16x32_bf16 v[2:5], v[180:183], v[232:235], v[2:5]
	s_barrier
	s_add_i32 s55, s55, 2
	s_add_u32 s8, s8, 0x100
	s_addc_u32 s9, s9, 0
	s_add_u32 s53, s53, 0x100
	s_addc_u32 s54, s54, 0
	s_cmp_gt_u32 s55, 13
	s_cbranch_scc0 .LBB0_809
	s_and_b64 vcc, exec, s[10:11]
	s_cbranch_vccz .LBB0_812
	s_barrier

.LBB0_1327:
	s_andn2_b64 vcc, exec, s[70:71]
	v_readfirstlane_b32 s0, v222
	s_cbranch_vccnz .LBB0_1431
	v_lshlrev_b32_e32 v0, 4, v222
	v_add_u32_e32 v2, 0x2000, v0
	v_ashrrev_i32_e32 v3, 31, v2
	v_lshrrev_b32_e32 v3, 22, v3
	v_add_u32_e32 v3, v2, v3
	v_ashrrev_i32_e32 v3, 10, v3
	s_waitcnt lgkmcnt(0)
	v_mul_i32_i24_e32 v4, 0x400, v3
	v_sub_u32_e32 v2, v2, v4
	v_lshrrev_b32_e32 v4, 4, v2
	v_bitop3_b32 v2, v4, v2, 32 bitop3:0x6c
	v_ashrrev_i32_e32 v4, 31, v2
	v_lshrrev_b32_e32 v4, 26, v4
	v_add_u32_e32 v4, v2, v4
	v_lshlrev_b32_e32 v6, 3, v3
	v_ashrrev_i32_e32 v5, 6, v4
	v_and_b32_e32 v6, -16, v6
	v_lshlrev_b32_e32 v3, 5, v3
	v_add_u32_e32 v6, v5, v6
	v_and_b32_e32 v14, 32, v3
	v_and_b32_e32 v3, 0xc0, v4
	v_and_b32_e32 v5, 3, v5
	s_mov_b32 s6, 0x7fffffe0
	v_lshrrev_b32_e32 v7, 2, v6
	v_lshlrev_b32_e32 v8, 1, v6
	v_sub_u32_e32 v2, v2, v3
	v_and_or_b32 v5, v6, s6, v5
	v_and_b32_e32 v7, 4, v7
	v_and_b32_e32 v8, 24, v8
	v_ashrrev_i16_sdwa v2, v241, sext(v2) dst_sel:DWORD dst_unused:UNUSED_PAD src0_sel:DWORD src1_sel:BYTE_0
	v_or3_b32 v5, v5, v7, v8
	v_bfe_i32 v15, v2, 0, 16
	v_mul_lo_u32 v5, s4, v5
	v_add_u32_e32 v2, v14, v15
	v_mul_lo_u32 v16, s14, v6
	v_add_lshl_u32 v160, v5, v2, 1
	v_add_lshl_u32 v170, v16, v2, 1
	v_bfe_i32 v2, v222, 27, 1
	v_lshrrev_b32_e32 v2, 22, v2
	v_add_u32_e32 v2, v0, v2
	v_and_b32_e32 v2, 0xfffffc00, v2
	v_sub_u32_e32 v0, v0, v2
	v_lshrrev_b32_e32 v2, 4, v0
	v_ashrrev_i32_e32 v4, 31, v222
	v_bitop3_b32 v0, v2, v0, 32 bitop3:0x6c
	v_lshrrev_b32_e32 v4, 26, v4
	v_ashrrev_i32_e32 v2, 31, v0
	v_add_u32_e32 v4, v222, v4
	v_lshrrev_b32_e32 v2, 26, v2
	v_ashrrev_i32_e32 v4, 6, v4
	v_add_u32_e32 v2, v0, v2
	v_lshlrev_b32_e32 v5, 3, v4
	v_ashrrev_i32_e32 v3, 6, v2
	v_and_b32_e32 v5, -16, v5
	s_lshl_b32 s10, s14, 8
	s_mov_b32 s11, s93
	v_add_u32_e32 v5, v3, v5
	v_and_b32_e32 v3, 3, v3
	s_lshl_b64 s[12:13], s[10:11], 1
	v_and_or_b32 v3, v5, s6, v3
	v_readlane_b32 s6, v253, 9
	s_mul_i32 s6, s12, s6
	s_mul_hi_u32 s7, s12, s76
	s_add_i32 s6, s7, s6
	s_bfe_u32 s7, s14, 0x10017
	s_mul_i32 s7, s7, s76
	v_and_b32_e32 v2, 0xc0, v2
	v_mul_lo_u32 v19, s14, v5
	s_add_i32 s14, s6, s7
	v_readlane_b32 s6, v253, 10
	s_ashr_i32 s5, s0, 6
	s_lshl_b32 s29, s4, 9
	v_lshrrev_b32_e32 v6, 2, v5
	v_lshlrev_b32_e32 v7, 1, v5
	v_sub_u32_e32 v0, v0, v2
	v_readlane_b32 s7, v253, 11
	s_mov_b32 s16, s6
	s_ashr_i32 s1, s0, 8
	s_lshl_b32 s28, s4, 8
	s_lshl_b32 s30, s5, 10
	v_and_b32_e32 v6, 4, v6
	v_and_b32_e32 v7, 24, v7
	v_lshlrev_b32_e32 v4, 5, v4
	v_ashrrev_i16_sdwa v0, v241, sext(v0) dst_sel:DWORD dst_unused:UNUSED_PAD src0_sel:DWORD src1_sel:BYTE_0
	s_mul_i32 s7, s29, s16
	v_or3_b32 v3, v3, v6, v7
	v_and_b32_e32 v17, 32, v4
	v_bfe_i32 v18, v0, 0, 16
	s_mul_hi_i32 s6, s29, s6
	s_add_u32 s24, s8, s7
	v_mul_lo_u32 v3, s4, v3
	v_add_u32_e32 v2, v17, v18
	s_addc_u32 s25, s9, s6
	s_add_i32 s31, s30, 0
	v_add_lshl_u32 v0, v3, v2, 1
	s_add_i32 m0, s31, 0x10000
	v_mov_b32_e32 v161, v1
	global_load_lds_dwordx4 v0, s[24:25]
	s_add_i32 m0, s31, 0x12000
	s_add_u32 s6, s24, s28
	global_load_lds_dwordx4 v160, s[24:25]
	s_addc_u32 s7, s25, 0
	s_add_i32 m0, s31, 0x14000
	s_mul_i32 s15, s12, s76
	global_load_lds_dwordx4 v0, s[6:7]
	s_add_i32 m0, s31, 0x16000
	v_lshl_add_u64 v[6:7], s[6:7], 0, v[0:1]
	v_lshl_add_u64 v[8:9], s[6:7], 0, v[160:161]
	global_load_lds_dwordx4 v160, s[6:7]
	v_readlane_b32 s6, v254, 32
	v_readlane_b32 s7, v254, 33
	s_add_u32 s26, s6, s15
	s_addc_u32 s27, s7, s14
	s_add_i32 s34, s31, 0x2000
	v_add_lshl_u32 v172, v19, v2, 1
	s_mov_b32 m0, s31
	s_add_u32 s6, s26, s10
	global_load_lds_dwordx4 v172, s[26:27]
	s_mov_b32 m0, s34
	s_addc_u32 s7, s27, 0
	s_add_i32 s35, s31, 0x4000
	global_load_lds_dwordx4 v170, s[26:27]
	s_mov_b32 m0, s35
	s_add_i32 s36, s31, 0x6000
	global_load_lds_dwordx4 v172, s[6:7]
	s_mov_b32 m0, s36
	v_mov_b32_e32 v173, v1
	global_load_lds_dwordx4 v170, s[6:7]
	v_mov_b32_e32 v171, v1
	s_cmp_eq_u32 s1, 1
	v_lshl_add_u64 v[2:3], s[24:25], 0, v[0:1]
	v_lshl_add_u64 v[4:5], s[24:25], 0, v[160:161]
	v_lshl_add_u64 v[10:11], s[26:27], 0, v[172:173]
	v_lshl_add_u64 v[12:13], s[26:27], 0, v[170:171]
	s_cselect_b64 s[14:15], -1, 0
	s_cmp_lg_u32 s1, 1
	s_cbranch_scc1 .LBB0_1330
	s_setprio 1
	s_barrier

.LBB0_1343:
	s_add_u32 s6, s26, 0x80
	s_addc_u32 s7, s27, 0
	s_add_u32 s26, s24, 0x100
	s_addc_u32 s27, s25, 0
	s_mov_b32 s24, 0
	s_add_i32 s47, s24, 2
	s_add_u32 s48, s6, 0x80
	s_addc_u32 s25, s7, 0
	s_add_i32 s50, 0, 0x10000
	s_cmp_eq_u32 s41, s24
	s_cselect_b32 s25, s21, s25
	s_cselect_b32 s24, s20, s48
	s_cselect_b32 s49, s23, s27
	s_cselect_b32 s48, s22, s26
	s_add_i32 s51, 0, 0x14000
	v_add_u32_e32 v142, s50, v197
	v_add_u32_e32 v162, s51, v197
	ds_read_b128 v[122:125], v142
	ds_read_b128 v[134:137], v142 offset:1024
	ds_read_b128 v[138:141], v142 offset:2048
	ds_read_b128 v[142:145], v142 offset:3072
	ds_read_b128 v[146:149], v162
	ds_read_b128 v[150:153], v162 offset:1024
	ds_read_b128 v[154:157], v162 offset:2048
	ds_read_b128 v[178:181], v162 offset:3072
	v_lshl_add_u64 v[162:163], s[6:7], 0, v[174:175]
	s_add_i32 m0, s31, 0xc000
	ds_read_b128 v[182:185], v199
	ds_read_b128 v[186:189], v199 offset:1024
	ds_read_b128 v[190:193], v199 offset:2048
	ds_read_b128 v[200:203], v199 offset:3072
	ds_read_b128 v[204:207], v199 offset:4096
	ds_read_b128 v[224:227], v199 offset:5120
	ds_read_b128 v[228:231], v199 offset:6144
	ds_read_b128 v[232:235], v199 offset:7168
	global_load_lds_dwordx4 v[162:163], off
	v_lshl_add_u64 v[162:163], s[6:7], 0, v[176:177]
	s_add_i32 m0, s31, 0xe000
	s_nop 0
	global_load_lds_dwordx4 v[162:163], off
	s_waitcnt vmcnt(16)
	s_waitcnt lgkmcnt(0)
	s_barrier
	s_waitcnt lgkmcnt(0)
	v_mfma_f32_16x16x32_bf16 v[130:133], v[122:125], v[182:185], 0
	v_mfma_f32_16x16x32_bf16 v[126:129], v[138:141], v[182:185], 0
	v_mfma_f32_16x16x32_bf16 v[110:113], v[122:125], v[190:193], 0
	v_mfma_f32_16x16x32_bf16 v[106:109], v[138:141], v[190:193], 0
	v_mfma_f32_16x16x32_bf16 v[94:97], v[122:125], v[204:207], 0
	v_mfma_f32_16x16x32_bf16 v[90:93], v[138:141], v[204:207], 0
	v_mfma_f32_16x16x32_bf16 v[78:81], v[122:125], v[228:231], 0
	v_mfma_f32_16x16x32_bf16 v[74:77], v[138:141], v[228:231], 0
	v_mfma_f32_16x16x32_bf16 v[130:133], v[134:137], v[186:189], v[130:133]
	v_mfma_f32_16x16x32_bf16 v[126:129], v[142:145], v[186:189], v[126:129]
	v_mfma_f32_16x16x32_bf16 v[110:113], v[134:137], v[200:203], v[110:113]
	v_mfma_f32_16x16x32_bf16 v[106:109], v[142:145], v[200:203], v[106:109]
	v_mfma_f32_16x16x32_bf16 v[94:97], v[134:137], v[224:227], v[94:97]
	v_mfma_f32_16x16x32_bf16 v[90:93], v[142:145], v[224:227], v[90:93]
	v_mfma_f32_16x16x32_bf16 v[78:81], v[134:137], v[232:235], v[78:81]
	v_mfma_f32_16x16x32_bf16 v[74:77], v[142:145], v[232:235], v[74:77]
	v_mfma_f32_16x16x32_bf16 v[118:121], v[146:149], v[182:185], 0
	v_mfma_f32_16x16x32_bf16 v[114:117], v[154:157], v[182:185], 0
	v_mfma_f32_16x16x32_bf16 v[102:105], v[146:149], v[190:193], 0
	v_mfma_f32_16x16x32_bf16 v[98:101], v[154:157], v[190:193], 0
	v_mfma_f32_16x16x32_bf16 v[86:89], v[146:149], v[204:207], 0
	v_mfma_f32_16x16x32_bf16 v[82:85], v[154:157], v[204:207], 0
	v_mfma_f32_16x16x32_bf16 v[70:73], v[146:149], v[228:231], 0
	v_mfma_f32_16x16x32_bf16 v[66:69], v[154:157], v[228:231], 0
	v_mfma_f32_16x16x32_bf16 v[118:121], v[150:153], v[186:189], v[118:121]
	v_mfma_f32_16x16x32_bf16 v[114:117], v[178:181], v[186:189], v[114:117]
	v_mfma_f32_16x16x32_bf16 v[102:105], v[150:153], v[200:203], v[102:105]
	v_mfma_f32_16x16x32_bf16 v[98:101], v[178:181], v[200:203], v[98:101]
	v_mfma_f32_16x16x32_bf16 v[86:89], v[150:153], v[224:227], v[86:89]
	v_mfma_f32_16x16x32_bf16 v[82:85], v[178:181], v[224:227], v[82:85]
	v_mfma_f32_16x16x32_bf16 v[70:73], v[150:153], v[232:235], v[70:73]
	v_mfma_f32_16x16x32_bf16 v[66:69], v[178:181], v[232:235], v[66:69]
	s_barrier
	s_add_i32 s50, s50, s30
	v_lshl_add_u64 v[162:163], s[48:49], 0, v[0:1]
	s_mov_b32 m0, s50
	ds_read_b128 v[182:185], v199 offset:16384
	ds_read_b128 v[186:189], v199 offset:17408
	ds_read_b128 v[190:193], v199 offset:18432
	ds_read_b128 v[200:203], v199 offset:19456
	ds_read_b128 v[204:207], v199 offset:20480
	ds_read_b128 v[224:227], v199 offset:21504
	ds_read_b128 v[228:231], v199 offset:22528
	ds_read_b128 v[232:235], v199 offset:23552
	global_load_lds_dwordx4 v[162:163], off
	s_add_i32 m0, s50, 0x2000
	v_lshl_add_u64 v[194:195], s[48:49], 0, v[160:161]
	s_add_u32 s48, s48, s28
	s_addc_u32 s49, s49, 0
	s_add_i32 s50, s51, s30
	global_load_lds_dwordx4 v[194:195], off
	v_lshl_add_u64 v[208:209], s[48:49], 0, v[0:1]
	s_mov_b32 m0, s50
	v_lshl_add_u64 v[214:215], s[48:49], 0, v[160:161]
	global_load_lds_dwordx4 v[208:209], off
	s_add_i32 m0, s50, 0x2000
	v_lshl_add_u64 v[216:217], s[24:25], 0, v[172:173]
	global_load_lds_dwordx4 v[214:215], off
	s_mov_b32 m0, s31
	v_lshl_add_u64 v[236:237], s[24:25], 0, v[170:171]
	global_load_lds_dwordx4 v[216:217], off
	s_mov_b32 m0, s34
	s_nop 0
	global_load_lds_dwordx4 v[236:237], off
	s_cmp_eq_u32 s42, 1
	s_cbranch_scc1 .Lrs_peel_w8
	s_waitcnt vmcnt(16)
	s_branch .Lrs_peel_wj

.Lrs_peel_wj:
	s_waitcnt lgkmcnt(0)
	s_barrier
	s_waitcnt lgkmcnt(0)
	v_mfma_f32_16x16x32_bf16 v[62:65], v[122:125], v[182:185], 0
	v_mfma_f32_16x16x32_bf16 v[58:61], v[138:141], v[182:185], 0
	v_mfma_f32_16x16x32_bf16 v[46:49], v[122:125], v[190:193], 0
	v_mfma_f32_16x16x32_bf16 v[42:45], v[138:141], v[190:193], 0
	v_mfma_f32_16x16x32_bf16 v[30:33], v[122:125], v[204:207], 0
	v_mfma_f32_16x16x32_bf16 v[26:29], v[138:141], v[204:207], 0
	v_mfma_f32_16x16x32_bf16 v[14:17], v[122:125], v[228:231], 0
	v_mfma_f32_16x16x32_bf16 v[10:13], v[138:141], v[228:231], 0
	v_mfma_f32_16x16x32_bf16 v[62:65], v[134:137], v[186:189], v[62:65]
	v_mfma_f32_16x16x32_bf16 v[58:61], v[142:145], v[186:189], v[58:61]
	v_mfma_f32_16x16x32_bf16 v[46:49], v[134:137], v[200:203], v[46:49]
	v_mfma_f32_16x16x32_bf16 v[42:45], v[142:145], v[200:203], v[42:45]
	v_mfma_f32_16x16x32_bf16 v[30:33], v[134:137], v[224:227], v[30:33]
	v_mfma_f32_16x16x32_bf16 v[26:29], v[142:145], v[224:227], v[26:29]
	v_mfma_f32_16x16x32_bf16 v[14:17], v[134:137], v[232:235], v[14:17]
	v_mfma_f32_16x16x32_bf16 v[10:13], v[142:145], v[232:235], v[10:13]
	v_mfma_f32_16x16x32_bf16 v[54:57], v[146:149], v[182:185], 0
	v_mfma_f32_16x16x32_bf16 v[50:53], v[154:157], v[182:185], 0
	v_mfma_f32_16x16x32_bf16 v[38:41], v[146:149], v[190:193], 0
	v_mfma_f32_16x16x32_bf16 v[34:37], v[154:157], v[190:193], 0
	v_mfma_f32_16x16x32_bf16 v[22:25], v[146:149], v[204:207], 0
	v_mfma_f32_16x16x32_bf16 v[18:21], v[154:157], v[204:207], 0
	v_mfma_f32_16x16x32_bf16 v[6:9], v[146:149], v[228:231], 0
	v_mfma_f32_16x16x32_bf16 v[2:5], v[154:157], v[228:231], 0
	v_mfma_f32_16x16x32_bf16 v[54:57], v[150:153], v[186:189], v[54:57]
	v_mfma_f32_16x16x32_bf16 v[50:53], v[178:181], v[186:189], v[50:53]
	v_mfma_f32_16x16x32_bf16 v[38:41], v[150:153], v[200:203], v[38:41]
	v_mfma_f32_16x16x32_bf16 v[34:37], v[178:181], v[200:203], v[34:37]
	v_mfma_f32_16x16x32_bf16 v[22:25], v[150:153], v[224:227], v[22:25]
	v_mfma_f32_16x16x32_bf16 v[18:21], v[178:181], v[224:227], v[18:21]
	v_mfma_f32_16x16x32_bf16 v[6:9], v[150:153], v[232:235], v[6:9]
	v_mfma_f32_16x16x32_bf16 v[2:5], v[178:181], v[232:235], v[2:5]
	s_barrier
	s_add_i32 s48, 0, 0x18000
	s_add_i32 s49, 0, 0x1c000
	v_add_u32_e32 v142, s48, v197
	v_add_u32_e32 v164, s49, v197
	ds_read_b128 v[122:125], v142
	ds_read_b128 v[134:137], v142 offset:1024
	ds_read_b128 v[138:141], v142 offset:2048
	ds_read_b128 v[142:145], v142 offset:3072
	ds_read_b128 v[146:149], v164
	ds_read_b128 v[150:153], v164 offset:1024
	ds_read_b128 v[154:157], v164 offset:2048
	ds_read_b128 v[178:181], v164 offset:3072
	s_add_u32 s24, s24, s10
	s_addc_u32 s25, s25, 0
	s_mov_b32 m0, s35
	v_lshl_add_u64 v[238:239], s[24:25], 0, v[172:173]
	ds_read_b128 v[182:185], v199 offset:32768
	ds_read_b128 v[186:189], v199 offset:33792
	ds_read_b128 v[190:193], v199 offset:34816
	ds_read_b128 v[200:203], v199 offset:35840
	ds_read_b128 v[204:207], v199 offset:36864
	ds_read_b128 v[224:227], v199 offset:37888
	ds_read_b128 v[228:231], v199 offset:38912
	ds_read_b128 v[232:235], v199 offset:39936
	global_load_lds_dwordx4 v[238:239], off
	v_lshl_add_u64 v[238:239], s[24:25], 0, v[170:171]
	s_mov_b32 m0, s36
	s_nop 0
	global_load_lds_dwordx4 v[238:239], off
	s_waitcnt vmcnt(8)
	s_waitcnt lgkmcnt(0)
	s_barrier
	s_waitcnt lgkmcnt(0)
	v_mfma_f32_16x16x32_bf16 v[130:133], v[122:125], v[182:185], v[130:133]
	v_mfma_f32_16x16x32_bf16 v[126:129], v[138:141], v[182:185], v[126:129]
	v_mfma_f32_16x16x32_bf16 v[110:113], v[122:125], v[190:193], v[110:113]
	v_mfma_f32_16x16x32_bf16 v[106:109], v[138:141], v[190:193], v[106:109]
	v_mfma_f32_16x16x32_bf16 v[94:97], v[122:125], v[204:207], v[94:97]
	v_mfma_f32_16x16x32_bf16 v[90:93], v[138:141], v[204:207], v[90:93]
	v_mfma_f32_16x16x32_bf16 v[78:81], v[122:125], v[228:231], v[78:81]
	v_mfma_f32_16x16x32_bf16 v[74:77], v[138:141], v[228:231], v[74:77]
	v_mfma_f32_16x16x32_bf16 v[130:133], v[134:137], v[186:189], v[130:133]
	v_mfma_f32_16x16x32_bf16 v[126:129], v[142:145], v[186:189], v[126:129]
	v_mfma_f32_16x16x32_bf16 v[110:113], v[134:137], v[200:203], v[110:113]
	v_mfma_f32_16x16x32_bf16 v[106:109], v[142:145], v[200:203], v[106:109]
	v_mfma_f32_16x16x32_bf16 v[94:97], v[134:137], v[224:227], v[94:97]
	v_mfma_f32_16x16x32_bf16 v[90:93], v[142:145], v[224:227], v[90:93]
	v_mfma_f32_16x16x32_bf16 v[78:81], v[134:137], v[232:235], v[78:81]
	v_mfma_f32_16x16x32_bf16 v[74:77], v[142:145], v[232:235], v[74:77]
	v_mfma_f32_16x16x32_bf16 v[118:121], v[146:149], v[182:185], v[118:121]
	v_mfma_f32_16x16x32_bf16 v[114:117], v[154:157], v[182:185], v[114:117]
	v_mfma_f32_16x16x32_bf16 v[102:105], v[146:149], v[190:193], v[102:105]
	v_mfma_f32_16x16x32_bf16 v[98:101], v[154:157], v[190:193], v[98:101]
	v_mfma_f32_16x16x32_bf16 v[86:89], v[146:149], v[204:207], v[86:89]
	v_mfma_f32_16x16x32_bf16 v[82:85], v[154:157], v[204:207], v[82:85]
	v_mfma_f32_16x16x32_bf16 v[70:73], v[146:149], v[228:231], v[70:73]
	v_mfma_f32_16x16x32_bf16 v[66:69], v[154:157], v[228:231], v[66:69]
	v_mfma_f32_16x16x32_bf16 v[118:121], v[150:153], v[186:189], v[118:121]
	v_mfma_f32_16x16x32_bf16 v[114:117], v[178:181], v[186:189], v[114:117]
	v_mfma_f32_16x16x32_bf16 v[102:105], v[150:153], v[200:203], v[102:105]
	v_mfma_f32_16x16x32_bf16 v[98:101], v[178:181], v[200:203], v[98:101]
	v_mfma_f32_16x16x32_bf16 v[86:89], v[150:153], v[224:227], v[86:89]
	v_mfma_f32_16x16x32_bf16 v[82:85], v[178:181], v[224:227], v[82:85]
	v_mfma_f32_16x16x32_bf16 v[70:73], v[150:153], v[232:235], v[70:73]
	v_mfma_f32_16x16x32_bf16 v[66:69], v[178:181], v[232:235], v[66:69]
	s_barrier
	s_add_i32 s24, s48, s30
	v_lshl_add_u64 v[162:163], v[162:163], 0, s[86:87]
	s_mov_b32 m0, s24
	ds_read_b128 v[182:185], v199 offset:49152
	ds_read_b128 v[186:189], v199 offset:50176
	ds_read_b128 v[190:193], v199 offset:51200
	ds_read_b128 v[200:203], v199 offset:52224
	ds_read_b128 v[204:207], v199 offset:53248
	ds_read_b128 v[224:227], v199 offset:54272
	ds_read_b128 v[228:231], v199 offset:55296
	ds_read_b128 v[232:235], v199 offset:56320
	global_load_lds_dwordx4 v[162:163], off
	v_lshl_add_u64 v[162:163], v[194:195], 0, s[86:87]
	s_add_i32 m0, s24, 0x2000
	s_add_i32 s24, s49, s30
	global_load_lds_dwordx4 v[162:163], off
	v_lshl_add_u64 v[162:163], v[208:209], 0, s[86:87]
	s_mov_b32 m0, s24
	s_nop 0
	global_load_lds_dwordx4 v[162:163], off
	v_lshl_add_u64 v[162:163], v[214:215], 0, s[86:87]
	s_add_i32 m0, s24, 0x2000
	s_nop 0
	global_load_lds_dwordx4 v[162:163], off
	v_lshl_add_u64 v[162:163], v[216:217], 0, s[86:87]
	s_mov_b32 m0, s37
	s_nop 0
	global_load_lds_dwordx4 v[162:163], off
	v_lshl_add_u64 v[162:163], v[236:237], 0, s[86:87]
	s_mov_b32 m0, s38
	s_nop 0
	global_load_lds_dwordx4 v[162:163], off
	s_waitcnt vmcnt(8)
	s_waitcnt lgkmcnt(0)
	s_barrier
	s_waitcnt lgkmcnt(0)
	v_mfma_f32_16x16x32_bf16 v[62:65], v[122:125], v[182:185], v[62:65]
	v_mfma_f32_16x16x32_bf16 v[58:61], v[138:141], v[182:185], v[58:61]
	v_mfma_f32_16x16x32_bf16 v[46:49], v[122:125], v[190:193], v[46:49]
	v_mfma_f32_16x16x32_bf16 v[42:45], v[138:141], v[190:193], v[42:45]
	v_mfma_f32_16x16x32_bf16 v[30:33], v[122:125], v[204:207], v[30:33]
	v_mfma_f32_16x16x32_bf16 v[26:29], v[138:141], v[204:207], v[26:29]
	v_mfma_f32_16x16x32_bf16 v[14:17], v[122:125], v[228:231], v[14:17]
	v_mfma_f32_16x16x32_bf16 v[10:13], v[138:141], v[228:231], v[10:13]
	v_mfma_f32_16x16x32_bf16 v[62:65], v[134:137], v[186:189], v[62:65]
	v_mfma_f32_16x16x32_bf16 v[58:61], v[142:145], v[186:189], v[58:61]
	v_mfma_f32_16x16x32_bf16 v[46:49], v[134:137], v[200:203], v[46:49]
	v_mfma_f32_16x16x32_bf16 v[42:45], v[142:145], v[200:203], v[42:45]
	v_mfma_f32_16x16x32_bf16 v[30:33], v[134:137], v[224:227], v[30:33]
	v_mfma_f32_16x16x32_bf16 v[26:29], v[142:145], v[224:227], v[26:29]
	v_mfma_f32_16x16x32_bf16 v[14:17], v[134:137], v[232:235], v[14:17]
	v_mfma_f32_16x16x32_bf16 v[10:13], v[142:145], v[232:235], v[10:13]
	v_mfma_f32_16x16x32_bf16 v[54:57], v[146:149], v[182:185], v[54:57]
	v_mfma_f32_16x16x32_bf16 v[50:53], v[154:157], v[182:185], v[50:53]
	v_mfma_f32_16x16x32_bf16 v[38:41], v[146:149], v[190:193], v[38:41]
	v_mfma_f32_16x16x32_bf16 v[34:37], v[154:157], v[190:193], v[34:37]
	v_mfma_f32_16x16x32_bf16 v[22:25], v[146:149], v[204:207], v[22:25]
	v_mfma_f32_16x16x32_bf16 v[18:21], v[154:157], v[204:207], v[18:21]
	v_mfma_f32_16x16x32_bf16 v[6:9], v[146:149], v[228:231], v[6:9]
	v_mfma_f32_16x16x32_bf16 v[2:5], v[154:157], v[228:231], v[2:5]
	v_mfma_f32_16x16x32_bf16 v[54:57], v[150:153], v[186:189], v[54:57]
	v_mfma_f32_16x16x32_bf16 v[50:53], v[178:181], v[186:189], v[50:53]
	v_mfma_f32_16x16x32_bf16 v[38:41], v[150:153], v[200:203], v[38:41]
	v_mfma_f32_16x16x32_bf16 v[34:37], v[178:181], v[200:203], v[34:37]
	v_mfma_f32_16x16x32_bf16 v[22:25], v[150:153], v[224:227], v[22:25]
	v_mfma_f32_16x16x32_bf16 v[18:21], v[178:181], v[224:227], v[18:21]
	v_mfma_f32_16x16x32_bf16 v[6:9], v[150:153], v[232:235], v[6:9]
	v_mfma_f32_16x16x32_bf16 v[2:5], v[178:181], v[232:235], v[2:5]
	s_barrier
	s_add_u32 s6, s6, 0x100
	s_addc_u32 s7, s7, 0
	s_add_u32 s26, s26, 0x100
	s_addc_u32 s27, s27, 0
	s_cmp_ge_u32 s47, s40
	s_mov_b32 s24, s47
	s_cbranch_scc0 .LBB0_1344
.LBB0_1344:
	s_add_i32 s47, s24, 2
	s_add_u32 s48, s6, 0x80
	s_addc_u32 s25, s7, 0
	s_add_i32 s50, 0, 0x10000
	s_cmp_eq_u32 s41, s24
	s_cselect_b32 s25, s21, s25
	s_cselect_b32 s24, s20, s48
	s_cselect_b32 s49, s23, s27
	s_cselect_b32 s48, s22, s26
	s_add_i32 s51, 0, 0x14000
	v_add_u32_e32 v142, s50, v197
	v_add_u32_e32 v162, s51, v197
	ds_read_b128 v[122:125], v142
	ds_read_b128 v[134:137], v142 offset:1024
	ds_read_b128 v[138:141], v142 offset:2048
	ds_read_b128 v[142:145], v142 offset:3072
	ds_read_b128 v[146:149], v162
	ds_read_b128 v[150:153], v162 offset:1024
	ds_read_b128 v[154:157], v162 offset:2048
	ds_read_b128 v[178:181], v162 offset:3072
	v_lshl_add_u64 v[162:163], s[6:7], 0, v[174:175]
	s_add_i32 m0, s31, 0xc000
	ds_read_b128 v[182:185], v199
	ds_read_b128 v[186:189], v199 offset:1024
	ds_read_b128 v[190:193], v199 offset:2048
	ds_read_b128 v[200:203], v199 offset:3072
	ds_read_b128 v[204:207], v199 offset:4096
	ds_read_b128 v[224:227], v199 offset:5120
	ds_read_b128 v[228:231], v199 offset:6144
	ds_read_b128 v[232:235], v199 offset:7168
	global_load_lds_dwordx4 v[162:163], off
	v_lshl_add_u64 v[162:163], s[6:7], 0, v[176:177]
	s_add_i32 m0, s31, 0xe000
	s_nop 0
	global_load_lds_dwordx4 v[162:163], off
	s_waitcnt vmcnt(8)
	s_waitcnt lgkmcnt(0)
	s_barrier
	s_waitcnt lgkmcnt(0)
	v_mfma_f32_16x16x32_bf16 v[130:133], v[122:125], v[182:185], v[130:133]
	v_mfma_f32_16x16x32_bf16 v[126:129], v[138:141], v[182:185], v[126:129]
	v_mfma_f32_16x16x32_bf16 v[110:113], v[122:125], v[190:193], v[110:113]
	v_mfma_f32_16x16x32_bf16 v[106:109], v[138:141], v[190:193], v[106:109]
	v_mfma_f32_16x16x32_bf16 v[94:97], v[122:125], v[204:207], v[94:97]
	v_mfma_f32_16x16x32_bf16 v[90:93], v[138:141], v[204:207], v[90:93]
	v_mfma_f32_16x16x32_bf16 v[78:81], v[122:125], v[228:231], v[78:81]
	v_mfma_f32_16x16x32_bf16 v[74:77], v[138:141], v[228:231], v[74:77]
	v_mfma_f32_16x16x32_bf16 v[130:133], v[134:137], v[186:189], v[130:133]
	v_mfma_f32_16x16x32_bf16 v[126:129], v[142:145], v[186:189], v[126:129]
	v_mfma_f32_16x16x32_bf16 v[110:113], v[134:137], v[200:203], v[110:113]
	v_mfma_f32_16x16x32_bf16 v[106:109], v[142:145], v[200:203], v[106:109]
	v_mfma_f32_16x16x32_bf16 v[94:97], v[134:137], v[224:227], v[94:97]
	v_mfma_f32_16x16x32_bf16 v[90:93], v[142:145], v[224:227], v[90:93]
	v_mfma_f32_16x16x32_bf16 v[78:81], v[134:137], v[232:235], v[78:81]
	v_mfma_f32_16x16x32_bf16 v[74:77], v[142:145], v[232:235], v[74:77]
	v_mfma_f32_16x16x32_bf16 v[118:121], v[146:149], v[182:185], v[118:121]
	v_mfma_f32_16x16x32_bf16 v[114:117], v[154:157], v[182:185], v[114:117]
	v_mfma_f32_16x16x32_bf16 v[102:105], v[146:149], v[190:193], v[102:105]
	v_mfma_f32_16x16x32_bf16 v[98:101], v[154:157], v[190:193], v[98:101]
	v_mfma_f32_16x16x32_bf16 v[86:89], v[146:149], v[204:207], v[86:89]
	v_mfma_f32_16x16x32_bf16 v[82:85], v[154:157], v[204:207], v[82:85]
	v_mfma_f32_16x16x32_bf16 v[70:73], v[146:149], v[228:231], v[70:73]
	v_mfma_f32_16x16x32_bf16 v[66:69], v[154:157], v[228:231], v[66:69]
	v_mfma_f32_16x16x32_bf16 v[118:121], v[150:153], v[186:189], v[118:121]
	v_mfma_f32_16x16x32_bf16 v[114:117], v[178:181], v[186:189], v[114:117]
	v_mfma_f32_16x16x32_bf16 v[102:105], v[150:153], v[200:203], v[102:105]
	v_mfma_f32_16x16x32_bf16 v[98:101], v[178:181], v[200:203], v[98:101]
	v_mfma_f32_16x16x32_bf16 v[86:89], v[150:153], v[224:227], v[86:89]
	v_mfma_f32_16x16x32_bf16 v[82:85], v[178:181], v[224:227], v[82:85]
	v_mfma_f32_16x16x32_bf16 v[70:73], v[150:153], v[232:235], v[70:73]
	v_mfma_f32_16x16x32_bf16 v[66:69], v[178:181], v[232:235], v[66:69]
	s_barrier
	s_add_i32 s50, s50, s30
	v_lshl_add_u64 v[162:163], s[48:49], 0, v[0:1]
	s_mov_b32 m0, s50
	ds_read_b128 v[182:185], v199 offset:16384
	ds_read_b128 v[186:189], v199 offset:17408
	ds_read_b128 v[190:193], v199 offset:18432
	ds_read_b128 v[200:203], v199 offset:19456
	ds_read_b128 v[204:207], v199 offset:20480
	ds_read_b128 v[224:227], v199 offset:21504
	ds_read_b128 v[228:231], v199 offset:22528
	ds_read_b128 v[232:235], v199 offset:23552
	global_load_lds_dwordx4 v[162:163], off
	s_add_i32 m0, s50, 0x2000
	v_lshl_add_u64 v[194:195], s[48:49], 0, v[160:161]
	s_add_u32 s48, s48, s28
	s_addc_u32 s49, s49, 0
	s_add_i32 s50, s51, s30
	global_load_lds_dwordx4 v[194:195], off
	v_lshl_add_u64 v[208:209], s[48:49], 0, v[0:1]
	s_mov_b32 m0, s50
	v_lshl_add_u64 v[214:215], s[48:49], 0, v[160:161]
	global_load_lds_dwordx4 v[208:209], off
	s_add_i32 m0, s50, 0x2000
	v_lshl_add_u64 v[216:217], s[24:25], 0, v[172:173]
	global_load_lds_dwordx4 v[214:215], off
	s_mov_b32 m0, s31
	v_lshl_add_u64 v[236:237], s[24:25], 0, v[170:171]
	global_load_lds_dwordx4 v[216:217], off
	s_mov_b32 m0, s34
	s_nop 0
	global_load_lds_dwordx4 v[236:237], off
	s_waitcnt vmcnt(8)
	s_waitcnt lgkmcnt(0)
	s_barrier
	s_waitcnt lgkmcnt(0)
	v_mfma_f32_16x16x32_bf16 v[62:65], v[122:125], v[182:185], v[62:65]
	v_mfma_f32_16x16x32_bf16 v[58:61], v[138:141], v[182:185], v[58:61]
	v_mfma_f32_16x16x32_bf16 v[46:49], v[122:125], v[190:193], v[46:49]
	v_mfma_f32_16x16x32_bf16 v[42:45], v[138:141], v[190:193], v[42:45]
	v_mfma_f32_16x16x32_bf16 v[30:33], v[122:125], v[204:207], v[30:33]
	v_mfma_f32_16x16x32_bf16 v[26:29], v[138:141], v[204:207], v[26:29]
	v_mfma_f32_16x16x32_bf16 v[14:17], v[122:125], v[228:231], v[14:17]
	v_mfma_f32_16x16x32_bf16 v[10:13], v[138:141], v[228:231], v[10:13]
	v_mfma_f32_16x16x32_bf16 v[62:65], v[134:137], v[186:189], v[62:65]
	v_mfma_f32_16x16x32_bf16 v[58:61], v[142:145], v[186:189], v[58:61]
	v_mfma_f32_16x16x32_bf16 v[46:49], v[134:137], v[200:203], v[46:49]
	v_mfma_f32_16x16x32_bf16 v[42:45], v[142:145], v[200:203], v[42:45]
	v_mfma_f32_16x16x32_bf16 v[30:33], v[134:137], v[224:227], v[30:33]
	v_mfma_f32_16x16x32_bf16 v[26:29], v[142:145], v[224:227], v[26:29]
	v_mfma_f32_16x16x32_bf16 v[14:17], v[134:137], v[232:235], v[14:17]
	v_mfma_f32_16x16x32_bf16 v[10:13], v[142:145], v[232:235], v[10:13]
	v_mfma_f32_16x16x32_bf16 v[54:57], v[146:149], v[182:185], v[54:57]
	v_mfma_f32_16x16x32_bf16 v[50:53], v[154:157], v[182:185], v[50:53]
	v_mfma_f32_16x16x32_bf16 v[38:41], v[146:149], v[190:193], v[38:41]
	v_mfma_f32_16x16x32_bf16 v[34:37], v[154:157], v[190:193], v[34:37]
	v_mfma_f32_16x16x32_bf16 v[22:25], v[146:149], v[204:207], v[22:25]
	v_mfma_f32_16x16x32_bf16 v[18:21], v[154:157], v[204:207], v[18:21]
	v_mfma_f32_16x16x32_bf16 v[6:9], v[146:149], v[228:231], v[6:9]
	v_mfma_f32_16x16x32_bf16 v[2:5], v[154:157], v[228:231], v[2:5]
	v_mfma_f32_16x16x32_bf16 v[54:57], v[150:153], v[186:189], v[54:57]
	v_mfma_f32_16x16x32_bf16 v[50:53], v[178:181], v[186:189], v[50:53]
	v_mfma_f32_16x16x32_bf16 v[38:41], v[150:153], v[200:203], v[38:41]
	v_mfma_f32_16x16x32_bf16 v[34:37], v[178:181], v[200:203], v[34:37]
	v_mfma_f32_16x16x32_bf16 v[22:25], v[150:153], v[224:227], v[22:25]
	v_mfma_f32_16x16x32_bf16 v[18:21], v[178:181], v[224:227], v[18:21]
	v_mfma_f32_16x16x32_bf16 v[6:9], v[150:153], v[232:235], v[6:9]
	v_mfma_f32_16x16x32_bf16 v[2:5], v[178:181], v[232:235], v[2:5]
	s_barrier
	s_add_i32 s48, 0, 0x18000
	s_add_i32 s49, 0, 0x1c000
	v_add_u32_e32 v142, s48, v197
	v_add_u32_e32 v164, s49, v197
	ds_read_b128 v[122:125], v142
	ds_read_b128 v[134:137], v142 offset:1024
	ds_read_b128 v[138:141], v142 offset:2048
	ds_read_b128 v[142:145], v142 offset:3072
	ds_read_b128 v[146:149], v164
	ds_read_b128 v[150:153], v164 offset:1024
	ds_read_b128 v[154:157], v164 offset:2048
	ds_read_b128 v[178:181], v164 offset:3072
	s_add_u32 s24, s24, s10
	s_addc_u32 s25, s25, 0
	s_mov_b32 m0, s35
	v_lshl_add_u64 v[238:239], s[24:25], 0, v[172:173]
	ds_read_b128 v[182:185], v199 offset:32768
	ds_read_b128 v[186:189], v199 offset:33792
	ds_read_b128 v[190:193], v199 offset:34816
	ds_read_b128 v[200:203], v199 offset:35840
	ds_read_b128 v[204:207], v199 offset:36864
	ds_read_b128 v[224:227], v199 offset:37888
	ds_read_b128 v[228:231], v199 offset:38912
	ds_read_b128 v[232:235], v199 offset:39936
	global_load_lds_dwordx4 v[238:239], off
	v_lshl_add_u64 v[238:239], s[24:25], 0, v[170:171]
	s_mov_b32 m0, s36
	s_nop 0
	global_load_lds_dwordx4 v[238:239], off
	s_waitcnt vmcnt(8)
	s_waitcnt lgkmcnt(0)
	s_barrier
	s_waitcnt lgkmcnt(0)
	v_mfma_f32_16x16x32_bf16 v[130:133], v[122:125], v[182:185], v[130:133]
	v_mfma_f32_16x16x32_bf16 v[126:129], v[138:141], v[182:185], v[126:129]
	v_mfma_f32_16x16x32_bf16 v[110:113], v[122:125], v[190:193], v[110:113]
	v_mfma_f32_16x16x32_bf16 v[106:109], v[138:141], v[190:193], v[106:109]
	v_mfma_f32_16x16x32_bf16 v[94:97], v[122:125], v[204:207], v[94:97]
	v_mfma_f32_16x16x32_bf16 v[90:93], v[138:141], v[204:207], v[90:93]
	v_mfma_f32_16x16x32_bf16 v[78:81], v[122:125], v[228:231], v[78:81]
	v_mfma_f32_16x16x32_bf16 v[74:77], v[138:141], v[228:231], v[74:77]
	v_mfma_f32_16x16x32_bf16 v[130:133], v[134:137], v[186:189], v[130:133]
	v_mfma_f32_16x16x32_bf16 v[126:129], v[142:145], v[186:189], v[126:129]
	v_mfma_f32_16x16x32_bf16 v[110:113], v[134:137], v[200:203], v[110:113]
	v_mfma_f32_16x16x32_bf16 v[106:109], v[142:145], v[200:203], v[106:109]
	v_mfma_f32_16x16x32_bf16 v[94:97], v[134:137], v[224:227], v[94:97]
	v_mfma_f32_16x16x32_bf16 v[90:93], v[142:145], v[224:227], v[90:93]
	v_mfma_f32_16x16x32_bf16 v[78:81], v[134:137], v[232:235], v[78:81]
	v_mfma_f32_16x16x32_bf16 v[74:77], v[142:145], v[232:235], v[74:77]
	v_mfma_f32_16x16x32_bf16 v[118:121], v[146:149], v[182:185], v[118:121]
	v_mfma_f32_16x16x32_bf16 v[114:117], v[154:157], v[182:185], v[114:117]
	v_mfma_f32_16x16x32_bf16 v[102:105], v[146:149], v[190:193], v[102:105]
	v_mfma_f32_16x16x32_bf16 v[98:101], v[154:157], v[190:193], v[98:101]
	v_mfma_f32_16x16x32_bf16 v[86:89], v[146:149], v[204:207], v[86:89]
	v_mfma_f32_16x16x32_bf16 v[82:85], v[154:157], v[204:207], v[82:85]
	v_mfma_f32_16x16x32_bf16 v[70:73], v[146:149], v[228:231], v[70:73]
	v_mfma_f32_16x16x32_bf16 v[66:69], v[154:157], v[228:231], v[66:69]
	v_mfma_f32_16x16x32_bf16 v[118:121], v[150:153], v[186:189], v[118:121]
	v_mfma_f32_16x16x32_bf16 v[114:117], v[178:181], v[186:189], v[114:117]
	v_mfma_f32_16x16x32_bf16 v[102:105], v[150:153], v[200:203], v[102:105]
	v_mfma_f32_16x16x32_bf16 v[98:101], v[178:181], v[200:203], v[98:101]
	v_mfma_f32_16x16x32_bf16 v[86:89], v[150:153], v[224:227], v[86:89]
	v_mfma_f32_16x16x32_bf16 v[82:85], v[178:181], v[224:227], v[82:85]
	v_mfma_f32_16x16x32_bf16 v[70:73], v[150:153], v[232:235], v[70:73]
	v_mfma_f32_16x16x32_bf16 v[66:69], v[178:181], v[232:235], v[66:69]
	s_barrier
	s_add_i32 s24, s48, s30
	v_lshl_add_u64 v[162:163], v[162:163], 0, s[86:87]
	s_mov_b32 m0, s24
	ds_read_b128 v[182:185], v199 offset:49152
	ds_read_b128 v[186:189], v199 offset:50176
	ds_read_b128 v[190:193], v199 offset:51200
	ds_read_b128 v[200:203], v199 offset:52224
	ds_read_b128 v[204:207], v199 offset:53248
	ds_read_b128 v[224:227], v199 offset:54272
	ds_read_b128 v[228:231], v199 offset:55296
	ds_read_b128 v[232:235], v199 offset:56320
	global_load_lds_dwordx4 v[162:163], off
	v_lshl_add_u64 v[162:163], v[194:195], 0, s[86:87]
	s_add_i32 m0, s24, 0x2000
	s_add_i32 s24, s49, s30
	global_load_lds_dwordx4 v[162:163], off
	v_lshl_add_u64 v[162:163], v[208:209], 0, s[86:87]
	s_mov_b32 m0, s24
	s_nop 0
	global_load_lds_dwordx4 v[162:163], off
	v_lshl_add_u64 v[162:163], v[214:215], 0, s[86:87]
	s_add_i32 m0, s24, 0x2000
	s_nop 0
	global_load_lds_dwordx4 v[162:163], off
	v_lshl_add_u64 v[162:163], v[216:217], 0, s[86:87]
	s_mov_b32 m0, s37
	s_nop 0
	global_load_lds_dwordx4 v[162:163], off
	v_lshl_add_u64 v[162:163], v[236:237], 0, s[86:87]
	s_mov_b32 m0, s38
	s_nop 0
	global_load_lds_dwordx4 v[162:163], off
	s_waitcnt vmcnt(8)
	s_waitcnt lgkmcnt(0)
	s_barrier
	s_waitcnt lgkmcnt(0)
	v_mfma_f32_16x16x32_bf16 v[62:65], v[122:125], v[182:185], v[62:65]
	v_mfma_f32_16x16x32_bf16 v[58:61], v[138:141], v[182:185], v[58:61]
	v_mfma_f32_16x16x32_bf16 v[46:49], v[122:125], v[190:193], v[46:49]
	v_mfma_f32_16x16x32_bf16 v[42:45], v[138:141], v[190:193], v[42:45]
	v_mfma_f32_16x16x32_bf16 v[30:33], v[122:125], v[204:207], v[30:33]
	v_mfma_f32_16x16x32_bf16 v[26:29], v[138:141], v[204:207], v[26:29]
	v_mfma_f32_16x16x32_bf16 v[14:17], v[122:125], v[228:231], v[14:17]
	v_mfma_f32_16x16x32_bf16 v[10:13], v[138:141], v[228:231], v[10:13]
	v_mfma_f32_16x16x32_bf16 v[62:65], v[134:137], v[186:189], v[62:65]
	v_mfma_f32_16x16x32_bf16 v[58:61], v[142:145], v[186:189], v[58:61]
	v_mfma_f32_16x16x32_bf16 v[46:49], v[134:137], v[200:203], v[46:49]
	v_mfma_f32_16x16x32_bf16 v[42:45], v[142:145], v[200:203], v[42:45]
	v_mfma_f32_16x16x32_bf16 v[30:33], v[134:137], v[224:227], v[30:33]
	v_mfma_f32_16x16x32_bf16 v[26:29], v[142:145], v[224:227], v[26:29]
	v_mfma_f32_16x16x32_bf16 v[14:17], v[134:137], v[232:235], v[14:17]
	v_mfma_f32_16x16x32_bf16 v[10:13], v[142:145], v[232:235], v[10:13]
	v_mfma_f32_16x16x32_bf16 v[54:57], v[146:149], v[182:185], v[54:57]
	v_mfma_f32_16x16x32_bf16 v[50:53], v[154:157], v[182:185], v[50:53]
	v_mfma_f32_16x16x32_bf16 v[38:41], v[146:149], v[190:193], v[38:41]
	v_mfma_f32_16x16x32_bf16 v[34:37], v[154:157], v[190:193], v[34:37]
	v_mfma_f32_16x16x32_bf16 v[22:25], v[146:149], v[204:207], v[22:25]
	v_mfma_f32_16x16x32_bf16 v[18:21], v[154:157], v[204:207], v[18:21]
	v_mfma_f32_16x16x32_bf16 v[6:9], v[146:149], v[228:231], v[6:9]
	v_mfma_f32_16x16x32_bf16 v[2:5], v[154:157], v[228:231], v[2:5]
	v_mfma_f32_16x16x32_bf16 v[54:57], v[150:153], v[186:189], v[54:57]
	v_mfma_f32_16x16x32_bf16 v[50:53], v[178:181], v[186:189], v[50:53]
	v_mfma_f32_16x16x32_bf16 v[38:41], v[150:153], v[200:203], v[38:41]
	v_mfma_f32_16x16x32_bf16 v[34:37], v[178:181], v[200:203], v[34:37]
	v_mfma_f32_16x16x32_bf16 v[22:25], v[150:153], v[224:227], v[22:25]
	v_mfma_f32_16x16x32_bf16 v[18:21], v[178:181], v[224:227], v[18:21]
	v_mfma_f32_16x16x32_bf16 v[6:9], v[150:153], v[232:235], v[6:9]
	v_mfma_f32_16x16x32_bf16 v[2:5], v[178:181], v[232:235], v[2:5]
	s_barrier
	s_add_u32 s6, s6, 0x100
	s_addc_u32 s7, s7, 0
	s_add_u32 s26, s26, 0x100
	s_addc_u32 s27, s27, 0
	s_cmp_ge_u32 s47, s40
	s_mov_b32 s24, s47
	s_cbranch_scc0 .LBB0_1344
	s_and_b64 vcc, exec, s[16:17]
	s_cbranch_vccz .LBB0_1347
	s_barrier

.LBB0_1432:
	s_and_b64 vcc, exec, s[2:3]
	s_cbranch_vccz .LBB0_1671
	s_mov_b32 s101, -1
	v_readlane_b32 s0, v254, 12
	v_readlane_b32 s1, v254, 13
	s_add_u32 s24, s0, 0x100000
	s_addc_u32 s25, s1, 0
	s_andn2_b64 vcc, exec, s[74:75]
	v_readfirstlane_b32 s0, v222
	s_cbranch_vccnz .LBB0_1453
	s_waitcnt vmcnt(0)
	v_lshlrev_b32_e32 v0, 4, v222
	v_add_u32_e32 v2, 0x2000, v0
	s_waitcnt lgkmcnt(0)
	v_ashrrev_i32_e32 v3, 31, v2
	v_lshrrev_b32_e32 v3, 22, v3
	v_add_u32_e32 v3, v2, v3
	v_ashrrev_i32_e32 v10, 10, v3
	v_mul_i32_i24_e32 v3, 0x400, v10
	v_sub_u32_e32 v2, v2, v3
	v_lshrrev_b32_e32 v3, 4, v2
	v_bitop3_b32 v2, v3, v2, 32 bitop3:0x6c
	v_ashrrev_i32_e32 v3, 31, v2
	v_lshrrev_b32_e32 v3, 26, v3
	v_add_u32_e32 v3, v2, v3
	v_lshlrev_b32_e32 v4, 3, v10
	v_ashrrev_i32_e32 v11, 6, v3
	v_and_b32_e32 v4, -16, v4
	v_readlane_b32 s1, v254, 19
	v_readlane_b32 s2, v254, 24
	v_add_u32_e32 v4, v11, v4
	s_or_b32 s1, s2, s1
	v_and_b32_e32 v5, 3, v11
	s_mov_b32 s2, 0x1fffe0
	v_lshrrev_b32_e32 v6, 2, v4
	v_lshlrev_b32_e32 v7, 1, v4
	v_and_b32_e32 v3, 0xc0, v3
	v_and_or_b32 v5, v4, s2, v5
	v_and_b32_e32 v6, 4, v6
	v_and_b32_e32 v7, 24, v7
	v_sub_u32_e32 v2, v2, v3
	v_or3_b32 v5, v5, v6, v7
	v_lshlrev_b32_e32 v6, 5, v10
	v_ashrrev_i16_sdwa v2, v241, sext(v2) dst_sel:DWORD dst_unused:UNUSED_PAD src0_sel:DWORD src1_sel:BYTE_0
	v_and_b32_e32 v6, 32, v6
	v_bfe_i32 v12, v2, 0, 16
	v_add_lshl_u32 v2, v6, v12, 1
	v_lshl_add_u32 v154, v5, 11, v2
	v_lshl_add_u32 v156, v4, 11, v2
	v_bfe_i32 v2, v222, 27, 1
	v_lshrrev_b32_e32 v2, 22, v2
	v_add_u32_e32 v2, v0, v2
	v_and_b32_e32 v2, 0xfffffc00, v2
	v_sub_u32_e32 v0, v0, v2
	v_lshrrev_b32_e32 v2, 4, v0
	v_ashrrev_i32_e32 v3, 31, v222
	v_bitop3_b32 v0, v2, v0, 32 bitop3:0x6c
	v_lshrrev_b32_e32 v3, 26, v3
	v_ashrrev_i32_e32 v2, 31, v0
	v_add_u32_e32 v3, v222, v3
	v_lshrrev_b32_e32 v2, 26, v2
	v_ashrrev_i32_e32 v14, 6, v3
	v_add_u32_e32 v2, v0, v2
	v_lshlrev_b32_e32 v3, 3, v14
	v_ashrrev_i32_e32 v13, 6, v2
	v_and_b32_e32 v3, -16, v3
	s_mul_i32 s1, s1, 0xb00000
	v_add_u32_e32 v3, v13, v3
	s_add_u32 s20, s24, s1
	v_and_b32_e32 v4, 3, v13
	v_lshrrev_b32_e32 v5, 2, v3
	v_lshlrev_b32_e32 v6, 1, v3
	v_and_b32_e32 v2, 0xc0, v2
	s_addc_u32 s21, s25, 0
	s_ashr_i32 s6, s0, 6
	v_and_or_b32 v4, v3, s2, v4
	v_and_b32_e32 v5, 4, v5
	v_and_b32_e32 v6, 24, v6
	v_sub_u32_e32 v0, v0, v2
	s_ashr_i32 s1, s0, 8
	s_lshl_b32 s22, s6, 10
	v_or3_b32 v4, v4, v5, v6
	v_lshlrev_b32_e32 v5, 5, v14
	v_ashrrev_i16_sdwa v0, v241, sext(v0) dst_sel:DWORD dst_unused:UNUSED_PAD src0_sel:DWORD src1_sel:BYTE_0
	v_and_b32_e32 v5, 32, v5
	v_bfe_i32 v15, v0, 0, 16
	s_add_u32 s16, s20, s82
	v_add_lshl_u32 v2, v5, v15, 1
	s_addc_u32 s17, s21, s83
	s_add_i32 s23, s22, 0
	v_lshl_add_u32 v0, v4, 11, v2
	s_add_i32 m0, s23, 0x10000
	v_lshl_add_u32 v158, v3, 11, v2
	global_load_lds_dwordx4 v0, s[16:17]
	s_add_i32 m0, s23, 0x12000
	s_add_u32 s2, s16, 0x40000
	global_load_lds_dwordx4 v154, s[16:17]
	s_addc_u32 s3, s17, 0
	s_add_i32 m0, s23, 0x14000
	v_mov_b32_e32 v155, v1
	global_load_lds_dwordx4 v0, s[2:3]
	s_add_i32 m0, s23, 0x16000
	v_mov_b32_e32 v159, v1
	global_load_lds_dwordx4 v154, s[2:3]
	v_readlane_b32 s2, v254, 28
	v_readlane_b32 s3, v254, 29
	s_add_u32 s4, s2, s80
	s_addc_u32 s5, s3, s81
	s_add_i32 s26, s23, 0x2000
	s_mov_b32 m0, s23
	s_add_u32 s2, s4, 0x40000
	global_load_lds_dwordx4 v158, s[4:5]
	s_mov_b32 m0, s26
	s_addc_u32 s3, s5, 0
	s_add_i32 s27, s23, 0x4000
	global_load_lds_dwordx4 v156, s[4:5]
	s_mov_b32 m0, s27
	s_add_i32 s28, s23, 0x6000
	global_load_lds_dwordx4 v158, s[2:3]
	s_mov_b32 m0, s28
	v_mov_b32_e32 v157, v1
	global_load_lds_dwordx4 v156, s[2:3]
	s_cmp_eq_u32 s1, 1
	v_lshl_add_u64 v[8:9], s[16:17], 0, v[0:1]
	v_lshl_add_u64 v[6:7], s[16:17], 0, v[154:155]
	v_lshl_add_u64 v[2:3], s[4:5], 0, v[158:159]
	s_cselect_b64 s[2:3], -1, 0
	s_cmp_lg_u32 s1, 1
	v_lshl_add_u64 v[4:5], s[4:5], 0, v[156:157]
	s_cbranch_scc1 .LBB0_1436
	s_setprio 1
	s_barrier

.Lgu_noy1:
	s_add_u32 s16, s4, 0xfffc0080
	s_addc_u32 s17, s5, -1
	s_add_i32 s42, 0, 0x10000
	s_cmp_eq_u32 s41, 12
	s_cselect_b32 s19, s11, s17
	s_cselect_b32 s18, s37, s16
	s_cselect_b32 s17, s9, s40
	s_cselect_b32 s16, s38, s39
	s_add_i32 s44, 0, 0x14000
	v_add_u32_e32 v142, s42, v195
	v_add_u32_e32 v162, s44, v195
	ds_read_b128 v[130:133], v142
	ds_read_b128 v[134:137], v142 offset:1024
	ds_read_b128 v[138:141], v142 offset:2048
	ds_read_b128 v[142:145], v142 offset:3072
	ds_read_b128 v[146:149], v162
	ds_read_b128 v[150:153], v162 offset:1024
	ds_read_b128 v[174:177], v162 offset:2048
	ds_read_b128 v[178:181], v162 offset:3072
	v_lshl_add_u64 v[162:163], s[4:5], 0, v[170:171]
	s_add_i32 m0, s23, 0xc000
	ds_read_b128 v[182:185], v199
	ds_read_b128 v[186:189], v199 offset:1024
	ds_read_b128 v[200:203], v199 offset:2048
	ds_read_b128 v[204:207], v199 offset:3072
	ds_read_b128 v[220:223], v199 offset:4096
	ds_read_b128 v[224:227], v199 offset:5120
	ds_read_b128 v[228:231], v199 offset:6144
	ds_read_b128 v[232:235], v199 offset:7168
	global_load_lds_dwordx4 v[162:163], off
	v_lshl_add_u64 v[162:163], s[4:5], 0, v[172:173]
	s_add_i32 m0, s23, 0xe000
	s_nop 0
	global_load_lds_dwordx4 v[162:163], off
	s_waitcnt vmcnt(16)
	s_waitcnt lgkmcnt(0)
	s_barrier
	s_waitcnt lgkmcnt(0)
	v_mfma_f32_16x16x32_bf16 v[126:129], v[130:133], v[182:185], 0
	v_mfma_f32_16x16x32_bf16 v[118:121], v[138:141], v[182:185], 0
	v_mfma_f32_16x16x32_bf16 v[110:113], v[130:133], v[200:203], 0
	v_mfma_f32_16x16x32_bf16 v[102:105], v[138:141], v[200:203], 0
	v_mfma_f32_16x16x32_bf16 v[94:97], v[130:133], v[220:223], 0
	v_mfma_f32_16x16x32_bf16 v[86:89], v[138:141], v[220:223], 0
	v_mfma_f32_16x16x32_bf16 v[78:81], v[130:133], v[228:231], 0
	v_mfma_f32_16x16x32_bf16 v[70:73], v[138:141], v[228:231], 0
	v_mfma_f32_16x16x32_bf16 v[126:129], v[134:137], v[186:189], v[126:129]
	v_mfma_f32_16x16x32_bf16 v[118:121], v[142:145], v[186:189], v[118:121]
	v_mfma_f32_16x16x32_bf16 v[110:113], v[134:137], v[204:207], v[110:113]
	v_mfma_f32_16x16x32_bf16 v[102:105], v[142:145], v[204:207], v[102:105]
	v_mfma_f32_16x16x32_bf16 v[94:97], v[134:137], v[224:227], v[94:97]
	v_mfma_f32_16x16x32_bf16 v[86:89], v[142:145], v[224:227], v[86:89]
	v_mfma_f32_16x16x32_bf16 v[78:81], v[134:137], v[232:235], v[78:81]
	v_mfma_f32_16x16x32_bf16 v[70:73], v[142:145], v[232:235], v[70:73]
	v_mfma_f32_16x16x32_bf16 v[122:125], v[146:149], v[182:185], 0
	v_mfma_f32_16x16x32_bf16 v[114:117], v[174:177], v[182:185], 0
	v_mfma_f32_16x16x32_bf16 v[106:109], v[146:149], v[200:203], 0
	v_mfma_f32_16x16x32_bf16 v[98:101], v[174:177], v[200:203], 0
	v_mfma_f32_16x16x32_bf16 v[90:93], v[146:149], v[220:223], 0
	v_mfma_f32_16x16x32_bf16 v[82:85], v[174:177], v[220:223], 0
	v_mfma_f32_16x16x32_bf16 v[74:77], v[146:149], v[228:231], 0
	v_mfma_f32_16x16x32_bf16 v[66:69], v[174:177], v[228:231], 0
	v_mfma_f32_16x16x32_bf16 v[122:125], v[150:153], v[186:189], v[122:125]
	v_mfma_f32_16x16x32_bf16 v[114:117], v[178:181], v[186:189], v[114:117]
	v_mfma_f32_16x16x32_bf16 v[106:109], v[150:153], v[204:207], v[106:109]
	v_mfma_f32_16x16x32_bf16 v[98:101], v[178:181], v[204:207], v[98:101]
	v_mfma_f32_16x16x32_bf16 v[90:93], v[150:153], v[224:227], v[90:93]
	v_mfma_f32_16x16x32_bf16 v[82:85], v[178:181], v[224:227], v[82:85]
	v_mfma_f32_16x16x32_bf16 v[74:77], v[150:153], v[232:235], v[74:77]
	v_mfma_f32_16x16x32_bf16 v[66:69], v[178:181], v[232:235], v[66:69]
	s_barrier
	s_add_i32 s42, s42, s22
	v_lshl_add_u64 v[162:163], s[16:17], 0, v[0:1]
	s_mov_b32 m0, s42
	ds_read_b128 v[182:185], v199 offset:16384
	ds_read_b128 v[186:189], v199 offset:17408
	ds_read_b128 v[200:203], v199 offset:18432
	ds_read_b128 v[204:207], v199 offset:19456
	ds_read_b128 v[220:223], v199 offset:20480
	ds_read_b128 v[224:227], v199 offset:21504
	ds_read_b128 v[228:231], v199 offset:22528
	ds_read_b128 v[232:235], v199 offset:23552
	global_load_lds_dwordx4 v[162:163], off
	s_add_i32 m0, s42, 0x2000
	s_add_u32 s42, s16, 0x40000
	v_lshl_add_u64 v[190:191], s[16:17], 0, v[154:155]
	s_addc_u32 s43, s17, 0
	s_add_i32 s44, s44, s22
	global_load_lds_dwordx4 v[190:191], off
	v_lshl_add_u64 v[196:197], s[42:43], 0, v[0:1]
	s_mov_b32 m0, s44
	v_lshl_add_u64 v[208:209], s[18:19], 0, v[156:157]
	global_load_lds_dwordx4 v[196:197], off
	v_lshl_add_u64 v[196:197], s[42:43], 0, v[154:155]
	s_add_i32 m0, s44, 0x2000
	s_nop 0
	global_load_lds_dwordx4 v[196:197], off
	v_lshl_add_u64 v[196:197], s[18:19], 0, v[158:159]
	s_mov_b32 m0, s23
	s_nop 0
	global_load_lds_dwordx4 v[196:197], off
	s_mov_b32 m0, s26
	s_nop 0
	global_load_lds_dwordx4 v[208:209], off
	s_cmp_eq_u32 s34, 1
	s_cbranch_scc1 .Lgu_peel_w8
	s_waitcnt vmcnt(16)
	s_branch .Lgu_peel_wj

.Lgu_peel_wj:
	s_waitcnt lgkmcnt(0)
	s_barrier
	s_waitcnt lgkmcnt(0)
	v_mfma_f32_16x16x32_bf16 v[62:65], v[130:133], v[182:185], 0
	v_mfma_f32_16x16x32_bf16 v[54:57], v[138:141], v[182:185], 0
	v_mfma_f32_16x16x32_bf16 v[46:49], v[130:133], v[200:203], 0
	v_mfma_f32_16x16x32_bf16 v[38:41], v[138:141], v[200:203], 0
	v_mfma_f32_16x16x32_bf16 v[30:33], v[130:133], v[220:223], 0
	v_mfma_f32_16x16x32_bf16 v[22:25], v[138:141], v[220:223], 0
	v_mfma_f32_16x16x32_bf16 v[14:17], v[130:133], v[228:231], 0
	v_mfma_f32_16x16x32_bf16 v[6:9], v[138:141], v[228:231], 0
	v_mfma_f32_16x16x32_bf16 v[62:65], v[134:137], v[186:189], v[62:65]
	v_mfma_f32_16x16x32_bf16 v[54:57], v[142:145], v[186:189], v[54:57]
	v_mfma_f32_16x16x32_bf16 v[46:49], v[134:137], v[204:207], v[46:49]
	v_mfma_f32_16x16x32_bf16 v[38:41], v[142:145], v[204:207], v[38:41]
	v_mfma_f32_16x16x32_bf16 v[30:33], v[134:137], v[224:227], v[30:33]
	v_mfma_f32_16x16x32_bf16 v[22:25], v[142:145], v[224:227], v[22:25]
	v_mfma_f32_16x16x32_bf16 v[14:17], v[134:137], v[232:235], v[14:17]
	v_mfma_f32_16x16x32_bf16 v[6:9], v[142:145], v[232:235], v[6:9]
	v_mfma_f32_16x16x32_bf16 v[58:61], v[146:149], v[182:185], 0
	v_mfma_f32_16x16x32_bf16 v[50:53], v[174:177], v[182:185], 0
	v_mfma_f32_16x16x32_bf16 v[42:45], v[146:149], v[200:203], 0
	v_mfma_f32_16x16x32_bf16 v[34:37], v[174:177], v[200:203], 0
	v_mfma_f32_16x16x32_bf16 v[26:29], v[146:149], v[220:223], 0
	v_mfma_f32_16x16x32_bf16 v[18:21], v[174:177], v[220:223], 0
	v_mfma_f32_16x16x32_bf16 v[10:13], v[146:149], v[228:231], 0
	v_mfma_f32_16x16x32_bf16 v[2:5], v[174:177], v[228:231], 0
	v_mfma_f32_16x16x32_bf16 v[58:61], v[150:153], v[186:189], v[58:61]
	v_mfma_f32_16x16x32_bf16 v[50:53], v[178:181], v[186:189], v[50:53]
	v_mfma_f32_16x16x32_bf16 v[42:45], v[150:153], v[204:207], v[42:45]
	v_mfma_f32_16x16x32_bf16 v[34:37], v[178:181], v[204:207], v[34:37]
	v_mfma_f32_16x16x32_bf16 v[26:29], v[150:153], v[224:227], v[26:29]
	v_mfma_f32_16x16x32_bf16 v[18:21], v[178:181], v[224:227], v[18:21]
	v_mfma_f32_16x16x32_bf16 v[10:13], v[150:153], v[232:235], v[10:13]
	v_mfma_f32_16x16x32_bf16 v[2:5], v[178:181], v[232:235], v[2:5]
	s_barrier
	s_add_i32 s42, 0, 0x18000
	s_add_i32 s43, 0, 0x1c000
	v_add_u32_e32 v142, s42, v195
	v_add_u32_e32 v164, s43, v195
	ds_read_b128 v[130:133], v142
	ds_read_b128 v[134:137], v142 offset:1024
	ds_read_b128 v[138:141], v142 offset:2048
	ds_read_b128 v[142:145], v142 offset:3072
	ds_read_b128 v[146:149], v164
	ds_read_b128 v[150:153], v164 offset:1024
	ds_read_b128 v[174:177], v164 offset:2048
	ds_read_b128 v[178:181], v164 offset:3072
	s_add_u32 s18, s18, 0x40000
	s_addc_u32 s19, s19, 0
	s_mov_b32 m0, s27
	v_lshl_add_u64 v[214:215], s[18:19], 0, v[158:159]
	ds_read_b128 v[182:185], v199 offset:32768
	ds_read_b128 v[186:189], v199 offset:33792
	ds_read_b128 v[200:203], v199 offset:34816
	ds_read_b128 v[204:207], v199 offset:35840
	ds_read_b128 v[220:223], v199 offset:36864
	ds_read_b128 v[224:227], v199 offset:37888
	ds_read_b128 v[228:231], v199 offset:38912
	ds_read_b128 v[232:235], v199 offset:39936
	global_load_lds_dwordx4 v[214:215], off
	v_lshl_add_u64 v[214:215], s[18:19], 0, v[156:157]
	s_mov_b32 m0, s28
	s_nop 0
	global_load_lds_dwordx4 v[214:215], off
	s_waitcnt vmcnt(8)
	s_waitcnt lgkmcnt(0)
	s_barrier
	s_waitcnt lgkmcnt(0)
	v_mfma_f32_16x16x32_bf16 v[126:129], v[130:133], v[182:185], v[126:129]
	v_mfma_f32_16x16x32_bf16 v[118:121], v[138:141], v[182:185], v[118:121]
	v_mfma_f32_16x16x32_bf16 v[110:113], v[130:133], v[200:203], v[110:113]
	v_mfma_f32_16x16x32_bf16 v[102:105], v[138:141], v[200:203], v[102:105]
	v_mfma_f32_16x16x32_bf16 v[94:97], v[130:133], v[220:223], v[94:97]
	v_mfma_f32_16x16x32_bf16 v[86:89], v[138:141], v[220:223], v[86:89]
	v_mfma_f32_16x16x32_bf16 v[78:81], v[130:133], v[228:231], v[78:81]
	v_mfma_f32_16x16x32_bf16 v[70:73], v[138:141], v[228:231], v[70:73]
	v_mfma_f32_16x16x32_bf16 v[126:129], v[134:137], v[186:189], v[126:129]
	v_mfma_f32_16x16x32_bf16 v[118:121], v[142:145], v[186:189], v[118:121]
	v_mfma_f32_16x16x32_bf16 v[110:113], v[134:137], v[204:207], v[110:113]
	v_mfma_f32_16x16x32_bf16 v[102:105], v[142:145], v[204:207], v[102:105]
	v_mfma_f32_16x16x32_bf16 v[94:97], v[134:137], v[224:227], v[94:97]
	v_mfma_f32_16x16x32_bf16 v[86:89], v[142:145], v[224:227], v[86:89]
	v_mfma_f32_16x16x32_bf16 v[78:81], v[134:137], v[232:235], v[78:81]
	v_mfma_f32_16x16x32_bf16 v[70:73], v[142:145], v[232:235], v[70:73]
	v_mfma_f32_16x16x32_bf16 v[122:125], v[146:149], v[182:185], v[122:125]
	v_mfma_f32_16x16x32_bf16 v[114:117], v[174:177], v[182:185], v[114:117]
	v_mfma_f32_16x16x32_bf16 v[106:109], v[146:149], v[200:203], v[106:109]
	v_mfma_f32_16x16x32_bf16 v[98:101], v[174:177], v[200:203], v[98:101]
	v_mfma_f32_16x16x32_bf16 v[90:93], v[146:149], v[220:223], v[90:93]
	v_mfma_f32_16x16x32_bf16 v[82:85], v[174:177], v[220:223], v[82:85]
	v_mfma_f32_16x16x32_bf16 v[74:77], v[146:149], v[228:231], v[74:77]
	v_mfma_f32_16x16x32_bf16 v[66:69], v[174:177], v[228:231], v[66:69]
	v_mfma_f32_16x16x32_bf16 v[122:125], v[150:153], v[186:189], v[122:125]
	v_mfma_f32_16x16x32_bf16 v[114:117], v[178:181], v[186:189], v[114:117]
	v_mfma_f32_16x16x32_bf16 v[106:109], v[150:153], v[204:207], v[106:109]
	v_mfma_f32_16x16x32_bf16 v[98:101], v[178:181], v[204:207], v[98:101]
	v_mfma_f32_16x16x32_bf16 v[90:93], v[150:153], v[224:227], v[90:93]
	v_mfma_f32_16x16x32_bf16 v[82:85], v[178:181], v[224:227], v[82:85]
	v_mfma_f32_16x16x32_bf16 v[74:77], v[150:153], v[232:235], v[74:77]
	v_mfma_f32_16x16x32_bf16 v[66:69], v[178:181], v[232:235], v[66:69]
	s_barrier
	s_add_i32 s18, s42, s22
	v_lshl_add_u64 v[162:163], v[162:163], 0, s[86:87]
	s_mov_b32 m0, s18
	ds_read_b128 v[182:185], v199 offset:49152
	ds_read_b128 v[186:189], v199 offset:50176
	ds_read_b128 v[200:203], v199 offset:51200
	ds_read_b128 v[204:207], v199 offset:52224
	ds_read_b128 v[220:223], v199 offset:53248
	ds_read_b128 v[224:227], v199 offset:54272
	ds_read_b128 v[228:231], v199 offset:55296
	ds_read_b128 v[232:235], v199 offset:56320
	global_load_lds_dwordx4 v[162:163], off
	s_add_i32 m0, s18, 0x2000
	s_add_u32 s16, s16, 0x40080
	v_lshl_add_u64 v[162:163], v[190:191], 0, s[86:87]
	s_addc_u32 s17, s17, 0
	s_add_i32 s18, s43, s22
	global_load_lds_dwordx4 v[162:163], off
	v_lshl_add_u64 v[162:163], s[16:17], 0, v[0:1]
	s_mov_b32 m0, s18
	s_nop 0
	global_load_lds_dwordx4 v[162:163], off
	v_lshl_add_u64 v[162:163], s[16:17], 0, v[154:155]
	s_add_i32 m0, s18, 0x2000
	s_nop 0
	global_load_lds_dwordx4 v[162:163], off
	v_lshl_add_u64 v[162:163], v[196:197], 0, s[86:87]
	s_mov_b32 m0, s29
	s_nop 0
	global_load_lds_dwordx4 v[162:163], off
	v_lshl_add_u64 v[162:163], v[208:209], 0, s[86:87]
	s_mov_b32 m0, s30
	s_nop 0
	global_load_lds_dwordx4 v[162:163], off
	s_waitcnt vmcnt(8)
	s_waitcnt lgkmcnt(0)
	s_barrier
	s_waitcnt lgkmcnt(0)
	v_mfma_f32_16x16x32_bf16 v[62:65], v[130:133], v[182:185], v[62:65]
	v_mfma_f32_16x16x32_bf16 v[54:57], v[138:141], v[182:185], v[54:57]
	v_mfma_f32_16x16x32_bf16 v[46:49], v[130:133], v[200:203], v[46:49]
	v_mfma_f32_16x16x32_bf16 v[38:41], v[138:141], v[200:203], v[38:41]
	v_mfma_f32_16x16x32_bf16 v[30:33], v[130:133], v[220:223], v[30:33]
	v_mfma_f32_16x16x32_bf16 v[22:25], v[138:141], v[220:223], v[22:25]
	v_mfma_f32_16x16x32_bf16 v[14:17], v[130:133], v[228:231], v[14:17]
	v_mfma_f32_16x16x32_bf16 v[6:9], v[138:141], v[228:231], v[6:9]
	v_mfma_f32_16x16x32_bf16 v[62:65], v[134:137], v[186:189], v[62:65]
	v_mfma_f32_16x16x32_bf16 v[54:57], v[142:145], v[186:189], v[54:57]
	v_mfma_f32_16x16x32_bf16 v[46:49], v[134:137], v[204:207], v[46:49]
	v_mfma_f32_16x16x32_bf16 v[38:41], v[142:145], v[204:207], v[38:41]
	v_mfma_f32_16x16x32_bf16 v[30:33], v[134:137], v[224:227], v[30:33]
	v_mfma_f32_16x16x32_bf16 v[22:25], v[142:145], v[224:227], v[22:25]
	v_mfma_f32_16x16x32_bf16 v[14:17], v[134:137], v[232:235], v[14:17]
	v_mfma_f32_16x16x32_bf16 v[6:9], v[142:145], v[232:235], v[6:9]
	v_mfma_f32_16x16x32_bf16 v[58:61], v[146:149], v[182:185], v[58:61]
	v_mfma_f32_16x16x32_bf16 v[50:53], v[174:177], v[182:185], v[50:53]
	v_mfma_f32_16x16x32_bf16 v[42:45], v[146:149], v[200:203], v[42:45]
	v_mfma_f32_16x16x32_bf16 v[34:37], v[174:177], v[200:203], v[34:37]
	v_mfma_f32_16x16x32_bf16 v[26:29], v[146:149], v[220:223], v[26:29]
	v_mfma_f32_16x16x32_bf16 v[18:21], v[174:177], v[220:223], v[18:21]
	v_mfma_f32_16x16x32_bf16 v[10:13], v[146:149], v[228:231], v[10:13]
	v_mfma_f32_16x16x32_bf16 v[2:5], v[174:177], v[228:231], v[2:5]
	v_mfma_f32_16x16x32_bf16 v[58:61], v[150:153], v[186:189], v[58:61]
	v_mfma_f32_16x16x32_bf16 v[50:53], v[178:181], v[186:189], v[50:53]
	v_mfma_f32_16x16x32_bf16 v[42:45], v[150:153], v[204:207], v[42:45]
	v_mfma_f32_16x16x32_bf16 v[34:37], v[178:181], v[204:207], v[34:37]
	v_mfma_f32_16x16x32_bf16 v[26:29], v[150:153], v[224:227], v[26:29]
	v_mfma_f32_16x16x32_bf16 v[18:21], v[178:181], v[224:227], v[18:21]
	v_mfma_f32_16x16x32_bf16 v[10:13], v[150:153], v[232:235], v[10:13]
	v_mfma_f32_16x16x32_bf16 v[2:5], v[178:181], v[232:235], v[2:5]
	s_barrier
	s_add_i32 s41, s41, 2
	s_add_u32 s4, s4, 0x100
	s_addc_u32 s5, s5, 0
	s_add_u32 s39, s39, 0x100
	s_addc_u32 s40, s40, 0
	s_cmp_gt_u32 s41, 13
	s_cbranch_scc0 .LBB0_1446
.LBB0_1446:
	s_add_u32 s16, s4, 0xfffc0080
	s_addc_u32 s17, s5, -1
	s_add_i32 s42, 0, 0x10000
	s_cmp_eq_u32 s41, 12
	s_cselect_b32 s19, s11, s17
	s_cselect_b32 s18, s37, s16
	s_cselect_b32 s17, s9, s40
	s_cselect_b32 s16, s38, s39
	s_add_i32 s44, 0, 0x14000
	v_add_u32_e32 v142, s42, v195
	v_add_u32_e32 v162, s44, v195
	ds_read_b128 v[130:133], v142
	ds_read_b128 v[134:137], v142 offset:1024
	ds_read_b128 v[138:141], v142 offset:2048
	ds_read_b128 v[142:145], v142 offset:3072
	ds_read_b128 v[146:149], v162
	ds_read_b128 v[150:153], v162 offset:1024
	ds_read_b128 v[174:177], v162 offset:2048
	ds_read_b128 v[178:181], v162 offset:3072
	v_lshl_add_u64 v[162:163], s[4:5], 0, v[170:171]
	s_add_i32 m0, s23, 0xc000
	ds_read_b128 v[182:185], v199
	ds_read_b128 v[186:189], v199 offset:1024
	ds_read_b128 v[200:203], v199 offset:2048
	ds_read_b128 v[204:207], v199 offset:3072
	ds_read_b128 v[220:223], v199 offset:4096
	ds_read_b128 v[224:227], v199 offset:5120
	ds_read_b128 v[228:231], v199 offset:6144
	ds_read_b128 v[232:235], v199 offset:7168
	global_load_lds_dwordx4 v[162:163], off
	v_lshl_add_u64 v[162:163], s[4:5], 0, v[172:173]
	s_add_i32 m0, s23, 0xe000
	s_nop 0
	global_load_lds_dwordx4 v[162:163], off
	s_waitcnt vmcnt(8)
	s_waitcnt lgkmcnt(0)
	s_barrier
	s_waitcnt lgkmcnt(0)
	v_mfma_f32_16x16x32_bf16 v[126:129], v[130:133], v[182:185], v[126:129]
	v_mfma_f32_16x16x32_bf16 v[118:121], v[138:141], v[182:185], v[118:121]
	v_mfma_f32_16x16x32_bf16 v[110:113], v[130:133], v[200:203], v[110:113]
	v_mfma_f32_16x16x32_bf16 v[102:105], v[138:141], v[200:203], v[102:105]
	v_mfma_f32_16x16x32_bf16 v[94:97], v[130:133], v[220:223], v[94:97]
	v_mfma_f32_16x16x32_bf16 v[86:89], v[138:141], v[220:223], v[86:89]
	v_mfma_f32_16x16x32_bf16 v[78:81], v[130:133], v[228:231], v[78:81]
	v_mfma_f32_16x16x32_bf16 v[70:73], v[138:141], v[228:231], v[70:73]
	v_mfma_f32_16x16x32_bf16 v[126:129], v[134:137], v[186:189], v[126:129]
	v_mfma_f32_16x16x32_bf16 v[118:121], v[142:145], v[186:189], v[118:121]
	v_mfma_f32_16x16x32_bf16 v[110:113], v[134:137], v[204:207], v[110:113]
	v_mfma_f32_16x16x32_bf16 v[102:105], v[142:145], v[204:207], v[102:105]
	v_mfma_f32_16x16x32_bf16 v[94:97], v[134:137], v[224:227], v[94:97]
	v_mfma_f32_16x16x32_bf16 v[86:89], v[142:145], v[224:227], v[86:89]
	v_mfma_f32_16x16x32_bf16 v[78:81], v[134:137], v[232:235], v[78:81]
	v_mfma_f32_16x16x32_bf16 v[70:73], v[142:145], v[232:235], v[70:73]
	v_mfma_f32_16x16x32_bf16 v[122:125], v[146:149], v[182:185], v[122:125]
	v_mfma_f32_16x16x32_bf16 v[114:117], v[174:177], v[182:185], v[114:117]
	v_mfma_f32_16x16x32_bf16 v[106:109], v[146:149], v[200:203], v[106:109]
	v_mfma_f32_16x16x32_bf16 v[98:101], v[174:177], v[200:203], v[98:101]
	v_mfma_f32_16x16x32_bf16 v[90:93], v[146:149], v[220:223], v[90:93]
	v_mfma_f32_16x16x32_bf16 v[82:85], v[174:177], v[220:223], v[82:85]
	v_mfma_f32_16x16x32_bf16 v[74:77], v[146:149], v[228:231], v[74:77]
	v_mfma_f32_16x16x32_bf16 v[66:69], v[174:177], v[228:231], v[66:69]
	v_mfma_f32_16x16x32_bf16 v[122:125], v[150:153], v[186:189], v[122:125]
	v_mfma_f32_16x16x32_bf16 v[114:117], v[178:181], v[186:189], v[114:117]
	v_mfma_f32_16x16x32_bf16 v[106:109], v[150:153], v[204:207], v[106:109]
	v_mfma_f32_16x16x32_bf16 v[98:101], v[178:181], v[204:207], v[98:101]
	v_mfma_f32_16x16x32_bf16 v[90:93], v[150:153], v[224:227], v[90:93]
	v_mfma_f32_16x16x32_bf16 v[82:85], v[178:181], v[224:227], v[82:85]
	v_mfma_f32_16x16x32_bf16 v[74:77], v[150:153], v[232:235], v[74:77]
	v_mfma_f32_16x16x32_bf16 v[66:69], v[178:181], v[232:235], v[66:69]
	s_barrier
	s_add_i32 s42, s42, s22
	v_lshl_add_u64 v[162:163], s[16:17], 0, v[0:1]
	s_mov_b32 m0, s42
	ds_read_b128 v[182:185], v199 offset:16384
	ds_read_b128 v[186:189], v199 offset:17408
	ds_read_b128 v[200:203], v199 offset:18432
	ds_read_b128 v[204:207], v199 offset:19456
	ds_read_b128 v[220:223], v199 offset:20480
	ds_read_b128 v[224:227], v199 offset:21504
	ds_read_b128 v[228:231], v199 offset:22528
	ds_read_b128 v[232:235], v199 offset:23552
	global_load_lds_dwordx4 v[162:163], off
	s_add_i32 m0, s42, 0x2000
	s_add_u32 s42, s16, 0x40000
	v_lshl_add_u64 v[190:191], s[16:17], 0, v[154:155]
	s_addc_u32 s43, s17, 0
	s_add_i32 s44, s44, s22
	global_load_lds_dwordx4 v[190:191], off
	v_lshl_add_u64 v[196:197], s[42:43], 0, v[0:1]
	s_mov_b32 m0, s44
	v_lshl_add_u64 v[208:209], s[18:19], 0, v[156:157]
	global_load_lds_dwordx4 v[196:197], off
	v_lshl_add_u64 v[196:197], s[42:43], 0, v[154:155]
	s_add_i32 m0, s44, 0x2000
	s_nop 0
	global_load_lds_dwordx4 v[196:197], off
	v_lshl_add_u64 v[196:197], s[18:19], 0, v[158:159]
	s_mov_b32 m0, s23
	s_nop 0
	global_load_lds_dwordx4 v[196:197], off
	s_mov_b32 m0, s26
	s_nop 0
	global_load_lds_dwordx4 v[208:209], off
	s_waitcnt vmcnt(8)
	s_waitcnt lgkmcnt(0)
	s_barrier
	s_waitcnt lgkmcnt(0)
	v_mfma_f32_16x16x32_bf16 v[62:65], v[130:133], v[182:185], v[62:65]
	v_mfma_f32_16x16x32_bf16 v[54:57], v[138:141], v[182:185], v[54:57]
	v_mfma_f32_16x16x32_bf16 v[46:49], v[130:133], v[200:203], v[46:49]
	v_mfma_f32_16x16x32_bf16 v[38:41], v[138:141], v[200:203], v[38:41]
	v_mfma_f32_16x16x32_bf16 v[30:33], v[130:133], v[220:223], v[30:33]
	v_mfma_f32_16x16x32_bf16 v[22:25], v[138:141], v[220:223], v[22:25]
	v_mfma_f32_16x16x32_bf16 v[14:17], v[130:133], v[228:231], v[14:17]
	v_mfma_f32_16x16x32_bf16 v[6:9], v[138:141], v[228:231], v[6:9]
	v_mfma_f32_16x16x32_bf16 v[62:65], v[134:137], v[186:189], v[62:65]
	v_mfma_f32_16x16x32_bf16 v[54:57], v[142:145], v[186:189], v[54:57]
	v_mfma_f32_16x16x32_bf16 v[46:49], v[134:137], v[204:207], v[46:49]
	v_mfma_f32_16x16x32_bf16 v[38:41], v[142:145], v[204:207], v[38:41]
	v_mfma_f32_16x16x32_bf16 v[30:33], v[134:137], v[224:227], v[30:33]
	v_mfma_f32_16x16x32_bf16 v[22:25], v[142:145], v[224:227], v[22:25]
	v_mfma_f32_16x16x32_bf16 v[14:17], v[134:137], v[232:235], v[14:17]
	v_mfma_f32_16x16x32_bf16 v[6:9], v[142:145], v[232:235], v[6:9]
	v_mfma_f32_16x16x32_bf16 v[58:61], v[146:149], v[182:185], v[58:61]
	v_mfma_f32_16x16x32_bf16 v[50:53], v[174:177], v[182:185], v[50:53]
	v_mfma_f32_16x16x32_bf16 v[42:45], v[146:149], v[200:203], v[42:45]
	v_mfma_f32_16x16x32_bf16 v[34:37], v[174:177], v[200:203], v[34:37]
	v_mfma_f32_16x16x32_bf16 v[26:29], v[146:149], v[220:223], v[26:29]
	v_mfma_f32_16x16x32_bf16 v[18:21], v[174:177], v[220:223], v[18:21]
	v_mfma_f32_16x16x32_bf16 v[10:13], v[146:149], v[228:231], v[10:13]
	v_mfma_f32_16x16x32_bf16 v[2:5], v[174:177], v[228:231], v[2:5]
	v_mfma_f32_16x16x32_bf16 v[58:61], v[150:153], v[186:189], v[58:61]
	v_mfma_f32_16x16x32_bf16 v[50:53], v[178:181], v[186:189], v[50:53]
	v_mfma_f32_16x16x32_bf16 v[42:45], v[150:153], v[204:207], v[42:45]
	v_mfma_f32_16x16x32_bf16 v[34:37], v[178:181], v[204:207], v[34:37]
	v_mfma_f32_16x16x32_bf16 v[26:29], v[150:153], v[224:227], v[26:29]
	v_mfma_f32_16x16x32_bf16 v[18:21], v[178:181], v[224:227], v[18:21]
	v_mfma_f32_16x16x32_bf16 v[10:13], v[150:153], v[232:235], v[10:13]
	v_mfma_f32_16x16x32_bf16 v[2:5], v[178:181], v[232:235], v[2:5]
	s_barrier
	s_add_i32 s42, 0, 0x18000
	s_add_i32 s43, 0, 0x1c000
	v_add_u32_e32 v142, s42, v195
	v_add_u32_e32 v164, s43, v195
	ds_read_b128 v[130:133], v142
	ds_read_b128 v[134:137], v142 offset:1024
	ds_read_b128 v[138:141], v142 offset:2048
	ds_read_b128 v[142:145], v142 offset:3072
	ds_read_b128 v[146:149], v164
	ds_read_b128 v[150:153], v164 offset:1024
	ds_read_b128 v[174:177], v164 offset:2048
	ds_read_b128 v[178:181], v164 offset:3072
	s_add_u32 s18, s18, 0x40000
	s_addc_u32 s19, s19, 0
	s_mov_b32 m0, s27
	v_lshl_add_u64 v[214:215], s[18:19], 0, v[158:159]
	ds_read_b128 v[182:185], v199 offset:32768
	ds_read_b128 v[186:189], v199 offset:33792
	ds_read_b128 v[200:203], v199 offset:34816
	ds_read_b128 v[204:207], v199 offset:35840
	ds_read_b128 v[220:223], v199 offset:36864
	ds_read_b128 v[224:227], v199 offset:37888
	ds_read_b128 v[228:231], v199 offset:38912
	ds_read_b128 v[232:235], v199 offset:39936
	global_load_lds_dwordx4 v[214:215], off
	v_lshl_add_u64 v[214:215], s[18:19], 0, v[156:157]
	s_mov_b32 m0, s28
	s_nop 0
	global_load_lds_dwordx4 v[214:215], off
	s_waitcnt vmcnt(8)
	s_waitcnt lgkmcnt(0)
	s_barrier
	s_waitcnt lgkmcnt(0)
	v_mfma_f32_16x16x32_bf16 v[126:129], v[130:133], v[182:185], v[126:129]
	v_mfma_f32_16x16x32_bf16 v[118:121], v[138:141], v[182:185], v[118:121]
	v_mfma_f32_16x16x32_bf16 v[110:113], v[130:133], v[200:203], v[110:113]
	v_mfma_f32_16x16x32_bf16 v[102:105], v[138:141], v[200:203], v[102:105]
	v_mfma_f32_16x16x32_bf16 v[94:97], v[130:133], v[220:223], v[94:97]
	v_mfma_f32_16x16x32_bf16 v[86:89], v[138:141], v[220:223], v[86:89]
	v_mfma_f32_16x16x32_bf16 v[78:81], v[130:133], v[228:231], v[78:81]
	v_mfma_f32_16x16x32_bf16 v[70:73], v[138:141], v[228:231], v[70:73]
	v_mfma_f32_16x16x32_bf16 v[126:129], v[134:137], v[186:189], v[126:129]
	v_mfma_f32_16x16x32_bf16 v[118:121], v[142:145], v[186:189], v[118:121]
	v_mfma_f32_16x16x32_bf16 v[110:113], v[134:137], v[204:207], v[110:113]
	v_mfma_f32_16x16x32_bf16 v[102:105], v[142:145], v[204:207], v[102:105]
	v_mfma_f32_16x16x32_bf16 v[94:97], v[134:137], v[224:227], v[94:97]
	v_mfma_f32_16x16x32_bf16 v[86:89], v[142:145], v[224:227], v[86:89]
	v_mfma_f32_16x16x32_bf16 v[78:81], v[134:137], v[232:235], v[78:81]
	v_mfma_f32_16x16x32_bf16 v[70:73], v[142:145], v[232:235], v[70:73]
	v_mfma_f32_16x16x32_bf16 v[122:125], v[146:149], v[182:185], v[122:125]
	v_mfma_f32_16x16x32_bf16 v[114:117], v[174:177], v[182:185], v[114:117]
	v_mfma_f32_16x16x32_bf16 v[106:109], v[146:149], v[200:203], v[106:109]
	v_mfma_f32_16x16x32_bf16 v[98:101], v[174:177], v[200:203], v[98:101]
	v_mfma_f32_16x16x32_bf16 v[90:93], v[146:149], v[220:223], v[90:93]
	v_mfma_f32_16x16x32_bf16 v[82:85], v[174:177], v[220:223], v[82:85]
	v_mfma_f32_16x16x32_bf16 v[74:77], v[146:149], v[228:231], v[74:77]
	v_mfma_f32_16x16x32_bf16 v[66:69], v[174:177], v[228:231], v[66:69]
	v_mfma_f32_16x16x32_bf16 v[122:125], v[150:153], v[186:189], v[122:125]
	v_mfma_f32_16x16x32_bf16 v[114:117], v[178:181], v[186:189], v[114:117]
	v_mfma_f32_16x16x32_bf16 v[106:109], v[150:153], v[204:207], v[106:109]
	v_mfma_f32_16x16x32_bf16 v[98:101], v[178:181], v[204:207], v[98:101]
	v_mfma_f32_16x16x32_bf16 v[90:93], v[150:153], v[224:227], v[90:93]
	v_mfma_f32_16x16x32_bf16 v[82:85], v[178:181], v[224:227], v[82:85]
	v_mfma_f32_16x16x32_bf16 v[74:77], v[150:153], v[232:235], v[74:77]
	v_mfma_f32_16x16x32_bf16 v[66:69], v[178:181], v[232:235], v[66:69]
	s_barrier
	s_add_i32 s18, s42, s22
	v_lshl_add_u64 v[162:163], v[162:163], 0, s[86:87]
	s_mov_b32 m0, s18
	ds_read_b128 v[182:185], v199 offset:49152
	ds_read_b128 v[186:189], v199 offset:50176
	ds_read_b128 v[200:203], v199 offset:51200
	ds_read_b128 v[204:207], v199 offset:52224
	ds_read_b128 v[220:223], v199 offset:53248
	ds_read_b128 v[224:227], v199 offset:54272
	ds_read_b128 v[228:231], v199 offset:55296
	ds_read_b128 v[232:235], v199 offset:56320
	global_load_lds_dwordx4 v[162:163], off
	s_add_i32 m0, s18, 0x2000
	s_add_u32 s16, s16, 0x40080
	v_lshl_add_u64 v[162:163], v[190:191], 0, s[86:87]
	s_addc_u32 s17, s17, 0
	s_add_i32 s18, s43, s22
	global_load_lds_dwordx4 v[162:163], off
	v_lshl_add_u64 v[162:163], s[16:17], 0, v[0:1]
	s_mov_b32 m0, s18
	s_nop 0
	global_load_lds_dwordx4 v[162:163], off
	v_lshl_add_u64 v[162:163], s[16:17], 0, v[154:155]
	s_add_i32 m0, s18, 0x2000
	s_nop 0
	global_load_lds_dwordx4 v[162:163], off
	v_lshl_add_u64 v[162:163], v[196:197], 0, s[86:87]
	s_mov_b32 m0, s29
	s_nop 0
	global_load_lds_dwordx4 v[162:163], off
	v_lshl_add_u64 v[162:163], v[208:209], 0, s[86:87]
	s_mov_b32 m0, s30
	s_nop 0
	global_load_lds_dwordx4 v[162:163], off
	s_waitcnt vmcnt(8)
	s_waitcnt lgkmcnt(0)
	s_barrier
	s_waitcnt lgkmcnt(0)
	v_mfma_f32_16x16x32_bf16 v[62:65], v[130:133], v[182:185], v[62:65]
	v_mfma_f32_16x16x32_bf16 v[54:57], v[138:141], v[182:185], v[54:57]
	v_mfma_f32_16x16x32_bf16 v[46:49], v[130:133], v[200:203], v[46:49]
	v_mfma_f32_16x16x32_bf16 v[38:41], v[138:141], v[200:203], v[38:41]
	v_mfma_f32_16x16x32_bf16 v[30:33], v[130:133], v[220:223], v[30:33]
	v_mfma_f32_16x16x32_bf16 v[22:25], v[138:141], v[220:223], v[22:25]
	v_mfma_f32_16x16x32_bf16 v[14:17], v[130:133], v[228:231], v[14:17]
	v_mfma_f32_16x16x32_bf16 v[6:9], v[138:141], v[228:231], v[6:9]
	v_mfma_f32_16x16x32_bf16 v[62:65], v[134:137], v[186:189], v[62:65]
	v_mfma_f32_16x16x32_bf16 v[54:57], v[142:145], v[186:189], v[54:57]
	v_mfma_f32_16x16x32_bf16 v[46:49], v[134:137], v[204:207], v[46:49]
	v_mfma_f32_16x16x32_bf16 v[38:41], v[142:145], v[204:207], v[38:41]
	v_mfma_f32_16x16x32_bf16 v[30:33], v[134:137], v[224:227], v[30:33]
	v_mfma_f32_16x16x32_bf16 v[22:25], v[142:145], v[224:227], v[22:25]
	v_mfma_f32_16x16x32_bf16 v[14:17], v[134:137], v[232:235], v[14:17]
	v_mfma_f32_16x16x32_bf16 v[6:9], v[142:145], v[232:235], v[6:9]
	v_mfma_f32_16x16x32_bf16 v[58:61], v[146:149], v[182:185], v[58:61]
	v_mfma_f32_16x16x32_bf16 v[50:53], v[174:177], v[182:185], v[50:53]
	v_mfma_f32_16x16x32_bf16 v[42:45], v[146:149], v[200:203], v[42:45]
	v_mfma_f32_16x16x32_bf16 v[34:37], v[174:177], v[200:203], v[34:37]
	v_mfma_f32_16x16x32_bf16 v[26:29], v[146:149], v[220:223], v[26:29]
	v_mfma_f32_16x16x32_bf16 v[18:21], v[174:177], v[220:223], v[18:21]
	v_mfma_f32_16x16x32_bf16 v[10:13], v[146:149], v[228:231], v[10:13]
	v_mfma_f32_16x16x32_bf16 v[2:5], v[174:177], v[228:231], v[2:5]
	v_mfma_f32_16x16x32_bf16 v[58:61], v[150:153], v[186:189], v[58:61]
	v_mfma_f32_16x16x32_bf16 v[50:53], v[178:181], v[186:189], v[50:53]
	v_mfma_f32_16x16x32_bf16 v[42:45], v[150:153], v[204:207], v[42:45]
	v_mfma_f32_16x16x32_bf16 v[34:37], v[178:181], v[204:207], v[34:37]
	v_mfma_f32_16x16x32_bf16 v[26:29], v[150:153], v[224:227], v[26:29]
	v_mfma_f32_16x16x32_bf16 v[18:21], v[178:181], v[224:227], v[18:21]
	v_mfma_f32_16x16x32_bf16 v[10:13], v[150:153], v[232:235], v[10:13]
	v_mfma_f32_16x16x32_bf16 v[2:5], v[178:181], v[232:235], v[2:5]
	s_barrier
	s_add_i32 s41, s41, 2
	s_add_u32 s4, s4, 0x100
	s_addc_u32 s5, s5, 0
	s_add_u32 s39, s39, 0x100
	s_addc_u32 s40, s40, 0
	s_cmp_gt_u32 s41, 13
	s_cbranch_scc0 .LBB0_1446

.LBB0_1671:
	s_setprio 0
	s_add_i32 s66, s66, 1
	s_cmp_ge_i32 s66, s67
	s_mov_b64 s[0:1], -1
	s_cbranch_scc0 .LBB0_1672
	s_getpc_b64 s[98:99]
